# EpiLn: residual loads 3-deep pipelined, gamma/beta loads hoisted
# baseline (speedup 1.0000x reference)
.LBB0_1116:
	s_add_i32 s3, s16, 0x200e8
	s_lshl_b32 s2, s44, 5
	v_mov_b32_e32 v0, s3
	s_lshl_b32 s3, s6, 8
	ds_read_b64 v[134:135], v0
	s_or_b32 s2, s3, s2
	v_lshrrev_b32_e32 v0, 2, v150
	s_lshl_b32 s4, s46, 8
	v_and_or_b32 v138, v0, 12, s2
	v_add_u32_e32 v140, s4, v154
	v_ashrrev_i32_e32 v139, 31, v138
	v_ashrrev_i32_e32 v141, 31, v140
	v_lshl_add_u64 v[136:137], v[138:139], 2, s[0:1]
	v_lshlrev_b64 v[94:95], 12, v[140:141]
	v_lshl_add_u64 v[152:153], v[136:137], 0, v[94:95]
	v_mov_b64_e32 v[246:247], v[152:153]
	global_load_dwordx4 v[182:185], v[246:247], off
	global_load_dwordx4 v[186:189], v[246:247], off offset:64
	global_load_dwordx4 v[190:193], v[246:247], off offset:512
	global_load_dwordx4 v[194:197], v[246:247], off offset:576
	s_mov_b32 s100, 0x10000
	s_mov_b32 s101, 0
	v_lshl_add_u64 v[230:231], v[246:247], 0, s[100:101]
	global_load_dwordx4 v[234:237], v[230:231], off offset:64
	global_load_dwordx4 v[238:241], v[230:231], off offset:512
	global_load_dwordx4 v[242:245], v[230:231], off offset:576
	global_load_dwordx4 v[230:233], v[230:231], off
	v_or_b32_e32 v152, 16, v140
	v_ashrrev_i32_e32 v153, 31, v152
	v_lshlrev_b64 v[152:153], 12, v[152:153]
	s_mov_b32 s0, 0x3fb504f3
	v_lshl_add_u64 v[152:153], v[136:137], 0, v[152:153]
	v_xor_b32_e32 v0, 16, v204
	s_waitcnt lgkmcnt(0)
	v_readfirstlane_b32 s23, v134
	v_readfirstlane_b32 s22, v135
	s_waitcnt vmcnt(4) lgkmcnt(0)
	v_pk_fma_f32 v[96:97], v[184:185], s[0:1], v[4:5] op_sel_hi:[1,0,1]
	v_pk_fma_f32 v[94:95], v[182:183], s[0:1], v[2:3] op_sel_hi:[1,0,1]
	v_pk_fma_f32 v[68:69], v[188:189], s[0:1], v[68:69] op_sel_hi:[1,0,1]
	v_pk_fma_f32 v[66:67], v[186:187], s[0:1], v[66:67] op_sel_hi:[1,0,1]
	v_pk_fma_f32 v[36:37], v[192:193], s[0:1], v[36:37] op_sel_hi:[1,0,1]
	v_pk_fma_f32 v[34:35], v[190:191], s[0:1], v[34:35] op_sel_hi:[1,0,1]
	v_pk_fma_f32 v[4:5], v[196:197], s[0:1], v[132:133] op_sel_hi:[1,0,1]
	v_pk_fma_f32 v[2:3], v[194:195], s[0:1], v[130:131] op_sel_hi:[1,0,1]
	s_nop 0
	s_mov_b32 s100, 0x20000
	s_mov_b32 s101, 0
	v_lshl_add_u64 v[156:157], v[246:247], 0, s[100:101]
	global_load_dwordx4 v[160:163], v[156:157], off offset:64
	global_load_dwordx4 v[164:167], v[156:157], off offset:512
	global_load_dwordx4 v[168:171], v[156:157], off offset:576
	global_load_dwordx4 v[156:159], v[156:157], off
	s_mov_b32 s100, 0x30000
	s_mov_b32 s101, 0
	v_lshl_add_u64 v[182:183], v[246:247], 0, s[100:101]
	global_load_dwordx4 v[186:189], v[182:183], off offset:64
	global_load_dwordx4 v[190:193], v[182:183], off offset:512
	global_load_dwordx4 v[194:197], v[182:183], off offset:576
	global_load_dwordx4 v[182:185], v[182:183], off
	v_or_b32_e32 v152, 32, v140
	v_ashrrev_i32_e32 v153, 31, v152
	v_lshlrev_b64 v[152:153], 12, v[152:153]
	v_lshl_add_u64 v[152:153], v[136:137], 0, v[152:153]
	v_mov_b32_e32 v172, v94
	v_mov_b32_e32 v173, v97
	v_mov_b32_e32 v174, v67
	v_mov_b32_e32 v175, v68
	v_mov_b32_e32 v176, v5
	s_waitcnt vmcnt(8) lgkmcnt(0)
	v_pk_fma_f32 v[104:105], v[232:233], s[0:1], v[104:105] op_sel_hi:[1,0,1]
	v_pk_fma_f32 v[102:103], v[230:231], s[0:1], v[102:103] op_sel_hi:[1,0,1]
	v_pk_fma_f32 v[72:73], v[236:237], s[0:1], v[72:73] op_sel_hi:[1,0,1]
	v_pk_fma_f32 v[70:71], v[234:235], s[0:1], v[70:71] op_sel_hi:[1,0,1]
	v_pk_fma_f32 v[40:41], v[240:241], s[0:1], v[40:41] op_sel_hi:[1,0,1]
	v_pk_fma_f32 v[38:39], v[238:239], s[0:1], v[38:39] op_sel_hi:[1,0,1]
	v_pk_fma_f32 v[8:9], v[244:245], s[0:1], v[8:9] op_sel_hi:[1,0,1]
	v_pk_fma_f32 v[6:7], v[242:243], s[0:1], v[6:7] op_sel_hi:[1,0,1]
	s_nop 0
	s_mov_b32 s100, 0x80000
	s_mov_b32 s101, 0
	v_lshl_add_u64 v[230:231], v[246:247], 0, s[100:101]
	global_load_dwordx4 v[234:237], v[230:231], off offset:64
	global_load_dwordx4 v[238:241], v[230:231], off offset:512
	global_load_dwordx4 v[242:245], v[230:231], off offset:576
	global_load_dwordx4 v[230:233], v[230:231], off
	v_or_b32_e32 v152, 48, v140
	v_ashrrev_i32_e32 v153, 31, v152
	v_lshlrev_b64 v[152:153], 12, v[152:153]
	v_lshl_add_u64 v[152:153], v[136:137], 0, v[152:153]
	s_waitcnt vmcnt(8) lgkmcnt(0)
	v_pk_fma_f32 v[108:109], v[158:159], s[0:1], v[108:109] op_sel_hi:[1,0,1]
	v_pk_fma_f32 v[106:107], v[156:157], s[0:1], v[106:107] op_sel_hi:[1,0,1]
	v_pk_fma_f32 v[76:77], v[162:163], s[0:1], v[76:77] op_sel_hi:[1,0,1]
	v_pk_fma_f32 v[74:75], v[160:161], s[0:1], v[74:75] op_sel_hi:[1,0,1]
	v_pk_fma_f32 v[44:45], v[166:167], s[0:1], v[44:45] op_sel_hi:[1,0,1]
	v_pk_fma_f32 v[42:43], v[164:165], s[0:1], v[42:43] op_sel_hi:[1,0,1]
	v_pk_fma_f32 v[12:13], v[170:171], s[0:1], v[12:13] op_sel_hi:[1,0,1]
	v_pk_fma_f32 v[10:11], v[168:169], s[0:1], v[10:11] op_sel_hi:[1,0,1]
	v_add_u32_e32 v142, 0x80, v140
	s_mov_b32 s100, 0x90000
	s_mov_b32 s101, 0
	v_lshl_add_u64 v[156:157], v[246:247], 0, s[100:101]
	global_load_dwordx4 v[160:163], v[156:157], off offset:64
	global_load_dwordx4 v[164:167], v[156:157], off offset:512
	global_load_dwordx4 v[168:171], v[156:157], off offset:576
	global_load_dwordx4 v[156:159], v[156:157], off
	v_ashrrev_i32_e32 v143, 31, v142
	v_lshlrev_b64 v[148:149], 12, v[142:143]
	v_lshl_add_u64 v[152:153], v[136:137], 0, v[148:149]
	s_waitcnt vmcnt(8) lgkmcnt(0)
	v_pk_fma_f32 v[112:113], v[184:185], s[0:1], v[112:113] op_sel_hi:[1,0,1]
	v_pk_fma_f32 v[110:111], v[182:183], s[0:1], v[110:111] op_sel_hi:[1,0,1]
	v_pk_fma_f32 v[80:81], v[188:189], s[0:1], v[80:81] op_sel_hi:[1,0,1]
	v_pk_fma_f32 v[78:79], v[186:187], s[0:1], v[78:79] op_sel_hi:[1,0,1]
	v_pk_fma_f32 v[48:49], v[192:193], s[0:1], v[48:49] op_sel_hi:[1,0,1]
	v_pk_fma_f32 v[46:47], v[190:191], s[0:1], v[46:47] op_sel_hi:[1,0,1]
	v_pk_fma_f32 v[16:17], v[196:197], s[0:1], v[16:17] op_sel_hi:[1,0,1]
	v_pk_fma_f32 v[14:15], v[194:195], s[0:1], v[14:15] op_sel_hi:[1,0,1]
	v_add_u32_e32 v144, 0x90, v140
	s_mov_b32 s100, 0xa0000
	s_mov_b32 s101, 0
	v_lshl_add_u64 v[182:183], v[246:247], 0, s[100:101]
	global_load_dwordx4 v[186:189], v[182:183], off offset:64
	global_load_dwordx4 v[190:193], v[182:183], off offset:512
	global_load_dwordx4 v[194:197], v[182:183], off offset:576
	global_load_dwordx4 v[182:185], v[182:183], off
	v_ashrrev_i32_e32 v145, 31, v144
	v_lshlrev_b64 v[152:153], 12, v[144:145]
	v_lshl_add_u64 v[152:153], v[136:137], 0, v[152:153]
	s_waitcnt vmcnt(8) lgkmcnt(0)
	v_pk_fma_f32 v[116:117], v[232:233], s[0:1], v[116:117] op_sel_hi:[1,0,1]
	v_pk_fma_f32 v[114:115], v[230:231], s[0:1], v[114:115] op_sel_hi:[1,0,1]
	v_pk_fma_f32 v[84:85], v[236:237], s[0:1], v[84:85] op_sel_hi:[1,0,1]
	v_pk_fma_f32 v[82:83], v[234:235], s[0:1], v[82:83] op_sel_hi:[1,0,1]
	v_pk_fma_f32 v[52:53], v[240:241], s[0:1], v[52:53] op_sel_hi:[1,0,1]
	v_pk_fma_f32 v[50:51], v[238:239], s[0:1], v[50:51] op_sel_hi:[1,0,1]
	v_pk_fma_f32 v[20:21], v[244:245], s[0:1], v[20:21] op_sel_hi:[1,0,1]
	v_pk_fma_f32 v[18:19], v[242:243], s[0:1], v[18:19] op_sel_hi:[1,0,1]
	v_add_u32_e32 v146, 0xa0, v140
	s_mov_b32 s100, 0xb0000
	s_mov_b32 s101, 0
	v_lshl_add_u64 v[230:231], v[246:247], 0, s[100:101]
	global_load_dwordx4 v[234:237], v[230:231], off offset:64
	global_load_dwordx4 v[238:241], v[230:231], off offset:512
	global_load_dwordx4 v[242:245], v[230:231], off offset:576
	global_load_dwordx4 v[230:233], v[230:231], off
	v_ashrrev_i32_e32 v147, 31, v146
	v_lshlrev_b64 v[148:149], 12, v[146:147]
	v_lshl_add_u64 v[148:149], v[136:137], 0, v[148:149]
	s_waitcnt vmcnt(8) lgkmcnt(0)
	v_pk_fma_f32 v[120:121], v[158:159], s[0:1], v[120:121] op_sel_hi:[1,0,1]
	v_pk_fma_f32 v[118:119], v[156:157], s[0:1], v[118:119] op_sel_hi:[1,0,1]
	v_pk_fma_f32 v[88:89], v[162:163], s[0:1], v[88:89] op_sel_hi:[1,0,1]
	v_pk_fma_f32 v[86:87], v[160:161], s[0:1], v[86:87] op_sel_hi:[1,0,1]
	v_pk_fma_f32 v[56:57], v[166:167], s[0:1], v[56:57] op_sel_hi:[1,0,1]
	v_pk_fma_f32 v[54:55], v[164:165], s[0:1], v[54:55] op_sel_hi:[1,0,1]
	v_pk_fma_f32 v[24:25], v[170:171], s[0:1], v[24:25] op_sel_hi:[1,0,1]
	v_pk_fma_f32 v[22:23], v[168:169], s[0:1], v[22:23] op_sel_hi:[1,0,1]
	s_nop 0
	v_and_b32_e32 v148, 64, v204
	v_add_u32_e32 v155, 64, v148
	v_add_u32_e32 v148, 0xb0, v140
	v_ashrrev_i32_e32 v149, 31, v148
	v_lshlrev_b64 v[152:153], 12, v[148:149]
	v_lshl_add_u64 v[136:137], v[136:137], 0, v[152:153]
	v_mov_b32_e32 v152, v95
	v_mov_b32_e32 v153, v96
	v_pk_add_f32 v[152:153], v[152:153], v[172:173]
	v_cmp_lt_i32_e32 vcc, v0, v155
	s_waitcnt vmcnt(4) lgkmcnt(0)
	v_pk_fma_f32 v[124:125], v[184:185], s[0:1], v[124:125] op_sel_hi:[1,0,1]
	v_pk_fma_f32 v[122:123], v[182:183], s[0:1], v[122:123] op_sel_hi:[1,0,1]
	v_pk_fma_f32 v[92:93], v[188:189], s[0:1], v[92:93] op_sel_hi:[1,0,1]
	v_pk_fma_f32 v[90:91], v[186:187], s[0:1], v[90:91] op_sel_hi:[1,0,1]
	v_pk_fma_f32 v[60:61], v[192:193], s[0:1], v[60:61] op_sel_hi:[1,0,1]
	v_pk_fma_f32 v[58:59], v[190:191], s[0:1], v[58:59] op_sel_hi:[1,0,1]
	v_pk_fma_f32 v[28:29], v[196:197], s[0:1], v[28:29] op_sel_hi:[1,0,1]
	v_pk_fma_f32 v[26:27], v[194:195], s[0:1], v[26:27] op_sel_hi:[1,0,1]
	v_mov_b32_e32 v130, v66
	v_mov_b32_e32 v131, v69
	v_add_f32_e32 v133, v34, v35
	v_add_f32_e32 v137, v36, v37
	v_mov_b32_e32 v132, v2
	v_mov_b32_e32 v136, v3
	v_pk_add_f32 v[130:131], v[174:175], v[130:131]
	v_pk_add_f32 v[132:133], v[132:133], v[136:137]
	v_add_f32_e32 v136, v152, v153
	v_pk_add_f32 v[130:131], v[130:131], v[130:131] op_sel_hi:[0,1]
	v_add_f32_e32 v177, 0, v136
	v_mov_b32_e32 v130, v4
	v_pk_add_f32 v[130:131], v[130:131], v[176:177]
	v_cndmask_b32_e32 v0, v204, v0, vcc
	v_pk_add_f32 v[130:131], v[132:133], v[130:131]
	v_lshlrev_b32_e32 v0, 2, v0
	v_add_f32_e32 v131, v130, v131
	ds_bpermute_b32 v132, v0, v131
	v_xor_b32_e32 v130, 32, v204
	v_cmp_lt_i32_e32 vcc, v130, v155
	s_waitcnt lgkmcnt(0)
	v_add_f32_e32 v131, v131, v132
	v_cndmask_b32_e32 v130, v204, v130, vcc
	v_lshlrev_b32_e32 v130, 2, v130
	ds_bpermute_b32 v132, v130, v131
	s_waitcnt lgkmcnt(0)
	v_add_f32_e32 v131, v131, v132
	v_fmamk_f32 v133, v131, 0xbc800000, v97
	v_fmamk_f32 v137, v131, 0xbc800000, v95
	v_fmamk_f32 v153, v131, 0xbc800000, v69
	v_fmamk_f32 v172, v131, 0xbc800000, v67
	v_fmamk_f32 v132, v131, 0xbc800000, v96
	v_fmamk_f32 v136, v131, 0xbc800000, v94
	v_fmamk_f32 v152, v131, 0xbc800000, v68
	v_fmamk_f32 v155, v131, 0xbc800000, v66
	v_fmamk_f32 v174, v131, 0xbc800000, v37
	v_fmamk_f32 v176, v131, 0xbc800000, v35
	v_mul_f32_e32 v137, v137, v137
	v_mul_f32_e32 v133, v133, v133
	v_mul_f32_e32 v172, v172, v172
	v_mul_f32_e32 v153, v153, v153
	v_fmamk_f32 v173, v131, 0xbc800000, v36
	v_fmamk_f32 v175, v131, 0xbc800000, v34
	v_fmamk_f32 v178, v131, 0xbc800000, v5
	v_fmamk_f32 v183, v131, 0xbc800000, v3
	v_mul_f32_e32 v176, v176, v176
	v_mul_f32_e32 v174, v174, v174
	v_fmac_f32_e32 v137, v136, v136
	v_fmac_f32_e32 v133, v132, v132
	v_fmac_f32_e32 v172, v155, v155
	v_fmac_f32_e32 v153, v152, v152
	v_fmamk_f32 v177, v131, 0xbc800000, v4
	v_fmamk_f32 v182, v131, 0xbc800000, v2
	v_mul_f32_e32 v183, v183, v183
	v_mul_f32_e32 v178, v178, v178
	v_fmac_f32_e32 v176, v175, v175
	v_fmac_f32_e32 v174, v173, v173
	v_add_f32_e32 v132, v137, v133
	v_add_f32_e32 v133, v172, v153
	v_fmac_f32_e32 v183, v182, v182
	v_fmac_f32_e32 v178, v177, v177
	v_add_f32_e32 v136, v176, v174
	v_add_f32_e32 v132, v132, v133
	v_add_f32_e32 v137, v183, v178
	v_add_f32_e32 v132, v136, v132
	v_add_f32_e32 v133, v137, v132
	ds_bpermute_b32 v136, v0, v133
	v_and_b32_e32 v132, 63, v150
	v_cmp_gt_u32_e32 vcc, 16, v132
	s_waitcnt lgkmcnt(0)
	v_add_f32_e32 v133, v133, v136
	ds_bpermute_b32 v134, v130, v133
	s_waitcnt vmcnt(0) lgkmcnt(0)
	v_pk_fma_f32 v[128:129], v[232:233], s[0:1], v[128:129] op_sel_hi:[1,0,1]
	v_pk_fma_f32 v[126:127], v[230:231], s[0:1], v[126:127] op_sel_hi:[1,0,1]
	v_pk_fma_f32 v[100:101], v[236:237], s[0:1], v[100:101] op_sel_hi:[1,0,1]
	v_pk_fma_f32 v[98:99], v[234:235], s[0:1], v[98:99] op_sel_hi:[1,0,1]
	v_pk_fma_f32 v[64:65], v[240:241], s[0:1], v[64:65] op_sel_hi:[1,0,1]
	v_pk_fma_f32 v[62:63], v[238:239], s[0:1], v[62:63] op_sel_hi:[1,0,1]
	v_pk_fma_f32 v[32:33], v[244:245], s[0:1], v[32:33] op_sel_hi:[1,0,1]
	v_pk_fma_f32 v[30:31], v[242:243], s[0:1], v[30:31] op_sel_hi:[1,0,1]
	s_lshl_b32 s0, s44, 3
	s_add_i32 s2, s14, s0
	s_and_saveexec_b64 s[0:1], vcc
	s_cbranch_execz .LBB0_1118
	s_lshl_b32 s3, s37, 11
	s_add_i32 s3, s2, s3
	v_mul_f32_e32 v136, 0x3c800000, v131
	s_waitcnt lgkmcnt(0)
	v_add_f32_e32 v137, v133, v134
	v_lshl_add_u32 v131, v151, 5, s3
	ds_write_b64 v131, v[136:137]

.LBB0_1155:
	s_or_b64 exec, exec, s[0:1]
	s_add_i32 s0, s16, 0x200a0
	s_waitcnt lgkmcnt(0)
	s_barrier
	v_mov_b32_e32 v0, s0
	ds_read_b64 v[130:131], v0
	v_readlane_b32 s0, v252, 6
	s_lshl_b32 s44, s0, 10
	s_lshl_b64 s[0:1], s[44:45], 2
	v_lshlrev_b64 v[132:133], 2, v[138:139]
	s_waitcnt lgkmcnt(0)
	v_readfirstlane_b32 s2, v130
	v_readfirstlane_b32 s3, v131
	s_add_u32 s2, s2, s0
	s_addc_u32 s3, s3, s1
	s_add_i32 s4, s16, 0x200a8
	v_mov_b32_e32 v0, s4
	ds_read_b64 v[130:131], v0
	v_lshl_add_u64 v[150:151], s[2:3], 0, v[132:133]
	v_lshl_add_u32 v0, v154, 3, s14
	v_lshlrev_b64 v[154:155], 10, v[140:141]
	v_add_u32_e32 v158, 16, v140
	s_waitcnt lgkmcnt(0)
	v_readfirstlane_b32 s3, v130
	v_readfirstlane_b32 s2, v131
	s_add_u32 s0, s3, s0
	s_addc_u32 s1, s2, s1
	v_lshl_add_u64 v[152:153], s[0:1], 0, v[132:133]
	flat_load_dwordx4 v[130:133], v[150:151]
	flat_load_dwordx4 v[134:137], v[152:153]
	global_load_dwordx4 v[182:185], v[150:151], off offset:64
	global_load_dwordx4 v[186:189], v[152:153], off offset:64
	global_load_dwordx4 v[190:193], v[150:151], off offset:512
	global_load_dwordx4 v[194:197], v[152:153], off offset:512
	global_load_dwordx4 v[218:221], v[150:151], off offset:576
	global_load_dwordx4 v[222:225], v[152:153], off offset:576
	ds_read_b64 v[164:165], v0 offset:8192
	v_add_u32_e32 v160, 32, v140
	v_add_u32_e32 v166, 48, v140
	v_lshl_add_u64 v[140:141], v[154:155], 0, v[138:139]
	s_add_u32 s0, s23, 0x4bf0000
	s_waitcnt lgkmcnt(0)
	v_sub_f32_e32 v97, v97, v164
	v_sub_f32_e32 v96, v96, v164
	v_sub_f32_e32 v95, v95, v164
	v_sub_f32_e32 v94, v94, v164
	v_pk_mul_f32 v[94:95], v[164:165], v[94:95] op_sel:[1,0]
	v_pk_mul_f32 v[96:97], v[164:165], v[96:97] op_sel:[1,0]
	v_cmp_eq_u32_e32 vcc, 0, v156
	v_lshl_add_u64 v[162:163], v[140:141], 2, s[8:9]
	s_addc_u32 s1, s22, 0
	v_lshl_add_u64 v[140:141], v[140:141], 1, s[0:1]
	v_ashrrev_i32_e32 v159, 31, v158
	v_lshlrev_b64 v[164:165], 10, v[158:159]
	v_ashrrev_i32_e32 v161, 31, v160
	v_lshlrev_b64 v[160:161], 10, v[160:161]
	v_ashrrev_i32_e32 v167, 31, v166
	v_lshlrev_b64 v[156:157], 10, v[166:167]
	v_lshlrev_b64 v[142:143], 10, v[142:143]
	v_lshlrev_b64 v[144:145], 10, v[144:145]
	s_waitcnt vmcnt(0)
	v_pk_fma_f32 v[96:97], v[132:133], v[96:97], v[136:137]
	v_pk_fma_f32 v[94:95], v[130:131], v[94:95], v[134:135]
	v_cndmask_b32_e32 v97, v211, v97, vcc
	v_cndmask_b32_e32 v96, v211, v96, vcc
	v_cndmask_b32_e32 v95, v211, v95, vcc
	v_cndmask_b32_e32 v94, v211, v94, vcc
	flat_store_dwordx4 v[162:163], v[94:97]
	s_nop 1
	v_cvt_pk_bf16_f32 v94, v94, v95
	v_cvt_pk_bf16_f32 v95, v96, v97
	flat_store_dwordx2 v[140:141], v[94:95]
	ds_read_b64 v[94:95], v0 offset:8320
	v_lshl_add_u64 v[96:97], v[164:165], 0, v[138:139]
	v_lshl_add_u64 v[158:159], v[96:97], 2, s[8:9]
	v_lshl_add_u64 v[140:141], v[96:97], 1, s[0:1]
	s_waitcnt lgkmcnt(0)
	v_sub_f32_e32 v97, v105, v94
	v_sub_f32_e32 v96, v104, v94
	v_sub_f32_e32 v103, v103, v94
	v_sub_f32_e32 v102, v102, v94
	v_pk_mul_f32 v[102:103], v[94:95], v[102:103] op_sel:[1,0]
	v_pk_mul_f32 v[94:95], v[94:95], v[96:97] op_sel:[1,0]
	v_pk_fma_f32 v[102:103], v[130:131], v[102:103], v[134:135]
	v_pk_fma_f32 v[94:95], v[132:133], v[94:95], v[136:137]
	s_nop 0
	v_cndmask_b32_e32 v97, v211, v95, vcc
	v_cndmask_b32_e32 v96, v211, v94, vcc
	v_cndmask_b32_e32 v95, v211, v103, vcc
	v_cndmask_b32_e32 v94, v211, v102, vcc
	flat_store_dwordx4 v[158:159], v[94:97]
	s_nop 1
	v_cvt_pk_bf16_f32 v94, v94, v95
	v_cvt_pk_bf16_f32 v95, v96, v97
	flat_store_dwordx2 v[140:141], v[94:95]
	ds_read_b64 v[94:95], v0 offset:8448
	v_lshl_add_u64 v[96:97], v[160:161], 0, v[138:139]
	v_lshl_add_u64 v[140:141], v[96:97], 2, s[8:9]
	v_lshl_add_u64 v[102:103], v[96:97], 1, s[0:1]
	s_waitcnt lgkmcnt(0)
	v_sub_f32_e32 v97, v109, v94
	v_sub_f32_e32 v96, v108, v94
	v_sub_f32_e32 v105, v107, v94
	v_sub_f32_e32 v104, v106, v94
	v_pk_mul_f32 v[104:105], v[94:95], v[104:105] op_sel:[1,0]
	v_pk_mul_f32 v[94:95], v[94:95], v[96:97] op_sel:[1,0]
	v_pk_fma_f32 v[104:105], v[130:131], v[104:105], v[134:135]
	v_pk_fma_f32 v[94:95], v[132:133], v[94:95], v[136:137]
	s_nop 0
	v_cndmask_b32_e32 v97, v211, v95, vcc
	v_cndmask_b32_e32 v96, v211, v94, vcc
	v_cndmask_b32_e32 v95, v211, v105, vcc
	v_cndmask_b32_e32 v94, v211, v104, vcc
	flat_store_dwordx4 v[140:141], v[94:97]
	s_nop 1
	v_cvt_pk_bf16_f32 v94, v94, v95
	v_cvt_pk_bf16_f32 v95, v96, v97
	flat_store_dwordx2 v[102:103], v[94:95]
	ds_read_b64 v[94:95], v0 offset:8576
	v_lshl_add_u64 v[96:97], v[156:157], 0, v[138:139]
	v_lshl_add_u64 v[106:107], v[96:97], 2, s[8:9]
	v_lshl_add_u64 v[102:103], v[96:97], 1, s[0:1]
	s_waitcnt lgkmcnt(0)
	v_sub_f32_e32 v97, v113, v94
	v_sub_f32_e32 v96, v112, v94
	v_sub_f32_e32 v105, v111, v94
	v_sub_f32_e32 v104, v110, v94
	v_pk_mul_f32 v[104:105], v[94:95], v[104:105] op_sel:[1,0]
	v_pk_mul_f32 v[94:95], v[94:95], v[96:97] op_sel:[1,0]
	v_pk_fma_f32 v[104:105], v[130:131], v[104:105], v[134:135]
	v_pk_fma_f32 v[94:95], v[132:133], v[94:95], v[136:137]
	s_nop 0
	v_cndmask_b32_e32 v97, v211, v95, vcc
	v_cndmask_b32_e32 v96, v211, v94, vcc
	v_cndmask_b32_e32 v95, v211, v105, vcc
	v_cndmask_b32_e32 v94, v211, v104, vcc
	flat_store_dwordx4 v[106:107], v[94:97]
	s_nop 1
	v_cvt_pk_bf16_f32 v94, v94, v95
	v_cvt_pk_bf16_f32 v95, v96, v97
	flat_store_dwordx2 v[102:103], v[94:95]
	ds_read_b64 v[94:95], v0 offset:9216
	v_lshl_add_u64 v[96:97], v[142:143], 0, v[138:139]
	v_lshl_add_u64 v[108:109], v[96:97], 2, s[8:9]
	v_lshl_add_u64 v[102:103], v[96:97], 1, s[0:1]
	s_waitcnt lgkmcnt(0)
	v_sub_f32_e32 v97, v117, v94
	v_sub_f32_e32 v96, v116, v94
	v_sub_f32_e32 v105, v115, v94
	v_sub_f32_e32 v104, v114, v94
	v_pk_mul_f32 v[104:105], v[94:95], v[104:105] op_sel:[1,0]
	v_pk_mul_f32 v[94:95], v[94:95], v[96:97] op_sel:[1,0]
	v_pk_fma_f32 v[104:105], v[130:131], v[104:105], v[134:135]
	v_pk_fma_f32 v[94:95], v[132:133], v[94:95], v[136:137]
	v_lshlrev_b64 v[116:117], 10, v[148:149]
	v_cndmask_b32_e32 v97, v211, v95, vcc
	v_cndmask_b32_e32 v96, v211, v94, vcc
	v_cndmask_b32_e32 v95, v211, v105, vcc
	v_cndmask_b32_e32 v94, v211, v104, vcc
	flat_store_dwordx4 v[108:109], v[94:97]
	s_nop 1
	v_cvt_pk_bf16_f32 v94, v94, v95
	v_cvt_pk_bf16_f32 v95, v96, v97
	flat_store_dwordx2 v[102:103], v[94:95]
	ds_read_b64 v[94:95], v0 offset:9344
	v_lshl_add_u64 v[102:103], v[144:145], 0, v[138:139]
	v_lshl_add_u64 v[112:113], v[102:103], 2, s[8:9]
	s_waitcnt lgkmcnt(0)
	v_sub_f32_e32 v97, v121, v94
	v_sub_f32_e32 v96, v120, v94
	v_sub_f32_e32 v105, v119, v94
	v_sub_f32_e32 v104, v118, v94
	v_pk_mul_f32 v[104:105], v[94:95], v[104:105] op_sel:[1,0]
	v_pk_mul_f32 v[94:95], v[94:95], v[96:97] op_sel:[1,0]
	v_pk_fma_f32 v[104:105], v[130:131], v[104:105], v[134:135]
	v_pk_fma_f32 v[94:95], v[132:133], v[94:95], v[136:137]
	v_lshlrev_b64 v[118:119], 10, v[146:147]
	v_cndmask_b32_e32 v97, v211, v95, vcc
	v_cndmask_b32_e32 v96, v211, v94, vcc
	v_cndmask_b32_e32 v95, v211, v105, vcc
	v_cndmask_b32_e32 v94, v211, v104, vcc
	flat_store_dwordx4 v[112:113], v[94:97]
	v_or_b32_e32 v120, 16, v138
	v_mov_b32_e32 v121, v139
	v_cvt_pk_bf16_f32 v94, v94, v95
	v_cvt_pk_bf16_f32 v95, v96, v97
	v_lshl_add_u64 v[96:97], v[102:103], 1, s[0:1]
	flat_store_dwordx2 v[96:97], v[94:95]
	ds_read_b64 v[94:95], v0 offset:9472
	v_lshl_add_u64 v[102:103], v[118:119], 0, v[138:139]
	v_lshl_add_u64 v[110:111], v[102:103], 2, s[8:9]
	s_waitcnt lgkmcnt(0)
	v_sub_f32_e32 v97, v125, v94
	v_sub_f32_e32 v96, v124, v94
	v_sub_f32_e32 v105, v123, v94
	v_sub_f32_e32 v104, v122, v94
	v_pk_mul_f32 v[104:105], v[94:95], v[104:105] op_sel:[1,0]
	v_pk_mul_f32 v[94:95], v[94:95], v[96:97] op_sel:[1,0]
	v_pk_fma_f32 v[104:105], v[130:131], v[104:105], v[134:135]
	v_pk_fma_f32 v[94:95], v[132:133], v[94:95], v[136:137]
	v_lshl_add_u64 v[124:125], v[154:155], 0, v[120:121]
	v_cndmask_b32_e32 v97, v211, v95, vcc
	v_cndmask_b32_e32 v96, v211, v94, vcc
	v_cndmask_b32_e32 v95, v211, v105, vcc
	v_cndmask_b32_e32 v94, v211, v104, vcc
	flat_store_dwordx4 v[110:111], v[94:97]
	v_lshl_add_u64 v[124:125], v[124:125], 1, s[0:1]
	s_nop 0
	v_cvt_pk_bf16_f32 v94, v94, v95
	v_cvt_pk_bf16_f32 v95, v96, v97
	v_lshl_add_u64 v[96:97], v[102:103], 1, s[0:1]
	flat_store_dwordx2 v[96:97], v[94:95]
	ds_read_b64 v[94:95], v0 offset:9600
	v_lshl_add_u64 v[102:103], v[116:117], 0, v[138:139]
	v_lshl_add_u64 v[114:115], v[102:103], 2, s[8:9]
	s_waitcnt lgkmcnt(0)
	v_sub_f32_e32 v97, v129, v94
	v_sub_f32_e32 v96, v128, v94
	v_sub_f32_e32 v105, v127, v94
	v_sub_f32_e32 v104, v126, v94
	v_pk_mul_f32 v[104:105], v[94:95], v[104:105] op_sel:[1,0]
	v_pk_mul_f32 v[94:95], v[94:95], v[96:97] op_sel:[1,0]
	v_pk_fma_f32 v[104:105], v[130:131], v[104:105], v[134:135]
	v_pk_fma_f32 v[94:95], v[132:133], v[94:95], v[136:137]
	s_nop 0
	v_cndmask_b32_e32 v97, v211, v95, vcc
	v_cndmask_b32_e32 v96, v211, v94, vcc
	v_cndmask_b32_e32 v95, v211, v105, vcc
	v_cndmask_b32_e32 v94, v211, v104, vcc
	flat_store_dwordx4 v[114:115], v[94:97]
	s_nop 1
	v_cvt_pk_bf16_f32 v94, v94, v95
	v_cvt_pk_bf16_f32 v95, v96, v97
	v_lshl_add_u64 v[96:97], v[102:103], 1, s[0:1]
	flat_store_dwordx2 v[96:97], v[94:95]
	s_nop 1
	v_mov_b32_e32 v94, v182
	v_mov_b32_e32 v95, v183
	v_mov_b32_e32 v96, v184
	v_mov_b32_e32 v97, v185
	s_nop 0
	s_nop 1
	v_mov_b32_e32 v102, v186
	v_mov_b32_e32 v103, v187
	v_mov_b32_e32 v104, v188
	v_mov_b32_e32 v105, v189
	ds_read_b64 v[122:123], v0 offset:8192
	s_waitcnt lgkmcnt(0)
	v_sub_f32_e32 v69, v69, v122
	v_sub_f32_e32 v68, v68, v122
	v_sub_f32_e32 v67, v67, v122
	v_sub_f32_e32 v66, v66, v122
	v_pk_mul_f32 v[66:67], v[122:123], v[66:67] op_sel:[1,0]
	v_pk_mul_f32 v[68:69], v[122:123], v[68:69] op_sel:[1,0]
	s_nop 0
	v_pk_fma_f32 v[66:67], v[94:95], v[66:67], v[102:103]
	v_pk_fma_f32 v[68:69], v[96:97], v[68:69], v[104:105]
	v_cndmask_b32_e32 v67, v211, v67, vcc
	v_cndmask_b32_e32 v69, v211, v69, vcc
	v_cndmask_b32_e32 v68, v211, v68, vcc
	v_cndmask_b32_e32 v66, v211, v66, vcc
	flat_store_dwordx4 v[162:163], v[66:69] offset:64
	s_nop 1
	v_cvt_pk_bf16_f32 v66, v66, v67
	v_cvt_pk_bf16_f32 v67, v68, v69
	flat_store_dwordx2 v[124:125], v[66:67]
	ds_read_b64 v[66:67], v0 offset:8320
	v_lshl_add_u64 v[68:69], v[164:165], 0, v[120:121]
	v_lshl_add_u64 v[122:123], v[68:69], 1, s[0:1]
	s_waitcnt lgkmcnt(0)
	v_sub_f32_e32 v69, v73, v66
	v_sub_f32_e32 v68, v72, v66
	v_sub_f32_e32 v71, v71, v66
	v_sub_f32_e32 v70, v70, v66
	v_pk_mul_f32 v[70:71], v[66:67], v[70:71] op_sel:[1,0]
	v_pk_mul_f32 v[66:67], v[66:67], v[68:69] op_sel:[1,0]
	v_pk_fma_f32 v[70:71], v[94:95], v[70:71], v[102:103]
	v_pk_fma_f32 v[66:67], v[96:97], v[66:67], v[104:105]
	s_nop 0
	v_cndmask_b32_e32 v69, v211, v67, vcc
	v_cndmask_b32_e32 v68, v211, v66, vcc
	v_cndmask_b32_e32 v67, v211, v71, vcc
	v_cndmask_b32_e32 v66, v211, v70, vcc
	flat_store_dwordx4 v[158:159], v[66:69] offset:64
	s_nop 1
	v_cvt_pk_bf16_f32 v66, v66, v67
	v_cvt_pk_bf16_f32 v67, v68, v69
	flat_store_dwordx2 v[122:123], v[66:67]
	ds_read_b64 v[66:67], v0 offset:8448
	v_lshl_add_u64 v[68:69], v[160:161], 0, v[120:121]
	v_lshl_add_u64 v[70:71], v[68:69], 1, s[0:1]
	s_waitcnt lgkmcnt(0)
	v_sub_f32_e32 v69, v77, v66
	v_sub_f32_e32 v68, v76, v66
	v_sub_f32_e32 v73, v75, v66
	v_sub_f32_e32 v72, v74, v66
	v_pk_mul_f32 v[72:73], v[66:67], v[72:73] op_sel:[1,0]
	v_pk_mul_f32 v[66:67], v[66:67], v[68:69] op_sel:[1,0]
	v_pk_fma_f32 v[72:73], v[94:95], v[72:73], v[102:103]
	v_pk_fma_f32 v[66:67], v[96:97], v[66:67], v[104:105]
	v_or_b32_e32 v74, 0x80, v138
	v_cndmask_b32_e32 v69, v211, v67, vcc
	v_cndmask_b32_e32 v68, v211, v66, vcc
	v_cndmask_b32_e32 v67, v211, v73, vcc
	v_cndmask_b32_e32 v66, v211, v72, vcc
	flat_store_dwordx4 v[140:141], v[66:69] offset:64
	v_mov_b32_e32 v75, v139
	v_or_b32_e32 v138, 0x90, v138
	v_cvt_pk_bf16_f32 v66, v66, v67
	v_cvt_pk_bf16_f32 v67, v68, v69
	flat_store_dwordx2 v[70:71], v[66:67]
	ds_read_b64 v[66:67], v0 offset:8576
	v_lshl_add_u64 v[68:69], v[156:157], 0, v[120:121]
	v_lshl_add_u64 v[70:71], v[68:69], 1, s[0:1]
	s_waitcnt lgkmcnt(0)
	v_sub_f32_e32 v69, v81, v66
	v_sub_f32_e32 v68, v80, v66
	v_sub_f32_e32 v73, v79, v66
	v_sub_f32_e32 v72, v78, v66
	v_pk_mul_f32 v[72:73], v[66:67], v[72:73] op_sel:[1,0]
	v_pk_mul_f32 v[66:67], v[66:67], v[68:69] op_sel:[1,0]
	v_pk_fma_f32 v[72:73], v[94:95], v[72:73], v[102:103]
	v_pk_fma_f32 v[66:67], v[96:97], v[66:67], v[104:105]
	v_lshl_add_u64 v[78:79], v[154:155], 0, v[74:75]
	v_cndmask_b32_e32 v69, v211, v67, vcc
	v_cndmask_b32_e32 v68, v211, v66, vcc
	v_cndmask_b32_e32 v67, v211, v73, vcc
	v_cndmask_b32_e32 v66, v211, v72, vcc
	flat_store_dwordx4 v[106:107], v[66:69] offset:64
	v_lshl_add_u64 v[78:79], v[78:79], 1, s[0:1]
	s_nop 0
	v_cvt_pk_bf16_f32 v66, v66, v67
	v_cvt_pk_bf16_f32 v67, v68, v69
	flat_store_dwordx2 v[70:71], v[66:67]
	ds_read_b64 v[66:67], v0 offset:9216
	v_lshl_add_u64 v[68:69], v[142:143], 0, v[120:121]
	v_lshl_add_u64 v[70:71], v[68:69], 1, s[0:1]
	s_waitcnt lgkmcnt(0)
	v_sub_f32_e32 v69, v85, v66
	v_sub_f32_e32 v68, v84, v66
	v_sub_f32_e32 v73, v83, v66
	v_sub_f32_e32 v72, v82, v66
	v_pk_mul_f32 v[72:73], v[66:67], v[72:73] op_sel:[1,0]
	v_pk_mul_f32 v[66:67], v[66:67], v[68:69] op_sel:[1,0]
	v_pk_fma_f32 v[72:73], v[94:95], v[72:73], v[102:103]
	v_pk_fma_f32 v[66:67], v[96:97], v[66:67], v[104:105]
	s_nop 0
	v_cndmask_b32_e32 v69, v211, v67, vcc
	v_cndmask_b32_e32 v68, v211, v66, vcc
	v_cndmask_b32_e32 v67, v211, v73, vcc
	v_cndmask_b32_e32 v66, v211, v72, vcc
	flat_store_dwordx4 v[108:109], v[66:69] offset:64
	s_nop 1
	v_cvt_pk_bf16_f32 v66, v66, v67
	v_cvt_pk_bf16_f32 v67, v68, v69
	flat_store_dwordx2 v[70:71], v[66:67]
	ds_read_b64 v[66:67], v0 offset:9344
	v_lshl_add_u64 v[68:69], v[144:145], 0, v[120:121]
	v_lshl_add_u64 v[70:71], v[68:69], 1, s[0:1]
	s_waitcnt lgkmcnt(0)
	v_sub_f32_e32 v69, v89, v66
	v_sub_f32_e32 v68, v88, v66
	v_sub_f32_e32 v73, v87, v66
	v_sub_f32_e32 v72, v86, v66
	v_pk_mul_f32 v[72:73], v[66:67], v[72:73] op_sel:[1,0]
	v_pk_mul_f32 v[66:67], v[66:67], v[68:69] op_sel:[1,0]
	v_pk_fma_f32 v[72:73], v[94:95], v[72:73], v[102:103]
	v_pk_fma_f32 v[66:67], v[96:97], v[66:67], v[104:105]
	s_nop 0
	v_cndmask_b32_e32 v69, v211, v67, vcc
	v_cndmask_b32_e32 v68, v211, v66, vcc
	v_cndmask_b32_e32 v67, v211, v73, vcc
	v_cndmask_b32_e32 v66, v211, v72, vcc
	flat_store_dwordx4 v[112:113], v[66:69] offset:64
	s_nop 1
	v_cvt_pk_bf16_f32 v66, v66, v67
	v_cvt_pk_bf16_f32 v67, v68, v69
	flat_store_dwordx2 v[70:71], v[66:67]
	ds_read_b64 v[66:67], v0 offset:9472
	v_lshl_add_u64 v[70:71], v[118:119], 0, v[120:121]
	s_waitcnt lgkmcnt(0)
	v_sub_f32_e32 v69, v93, v66
	v_sub_f32_e32 v68, v92, v66
	v_sub_f32_e32 v73, v91, v66
	v_sub_f32_e32 v72, v90, v66
	v_pk_mul_f32 v[72:73], v[66:67], v[72:73] op_sel:[1,0]
	v_pk_mul_f32 v[66:67], v[66:67], v[68:69] op_sel:[1,0]
	v_pk_fma_f32 v[72:73], v[94:95], v[72:73], v[102:103]
	v_pk_fma_f32 v[66:67], v[96:97], v[66:67], v[104:105]
	s_nop 0
	v_cndmask_b32_e32 v69, v211, v67, vcc
	v_cndmask_b32_e32 v68, v211, v66, vcc
	v_cndmask_b32_e32 v67, v211, v73, vcc
	v_cndmask_b32_e32 v66, v211, v72, vcc
	flat_store_dwordx4 v[110:111], v[66:69] offset:64
	s_nop 1
	v_cvt_pk_bf16_f32 v66, v66, v67
	v_cvt_pk_bf16_f32 v67, v68, v69
	v_lshl_add_u64 v[68:69], v[70:71], 1, s[0:1]
	flat_store_dwordx2 v[68:69], v[66:67]
	ds_read_b64 v[66:67], v0 offset:9600
	v_lshl_add_u64 v[70:71], v[116:117], 0, v[120:121]
	s_waitcnt lgkmcnt(0)
	v_sub_f32_e32 v69, v101, v66
	v_sub_f32_e32 v68, v100, v66
	v_sub_f32_e32 v73, v99, v66
	v_sub_f32_e32 v72, v98, v66
	v_pk_mul_f32 v[72:73], v[66:67], v[72:73] op_sel:[1,0]
	v_pk_mul_f32 v[66:67], v[66:67], v[68:69] op_sel:[1,0]
	v_pk_fma_f32 v[72:73], v[94:95], v[72:73], v[102:103]
	v_pk_fma_f32 v[66:67], v[96:97], v[66:67], v[104:105]
	s_nop 0
	v_cndmask_b32_e32 v69, v211, v67, vcc
	v_cndmask_b32_e32 v68, v211, v66, vcc
	v_cndmask_b32_e32 v67, v211, v73, vcc
	v_cndmask_b32_e32 v66, v211, v72, vcc
	flat_store_dwordx4 v[114:115], v[66:69] offset:64
	s_nop 1
	v_cvt_pk_bf16_f32 v66, v66, v67
	v_cvt_pk_bf16_f32 v67, v68, v69
	v_lshl_add_u64 v[68:69], v[70:71], 1, s[0:1]
	flat_store_dwordx2 v[68:69], v[66:67]
	s_nop 1
	v_mov_b32_e32 v66, v190
	v_mov_b32_e32 v67, v191
	v_mov_b32_e32 v68, v192
	v_mov_b32_e32 v69, v193
	s_nop 0
	s_nop 1
	v_mov_b32_e32 v70, v194
	v_mov_b32_e32 v71, v195
	v_mov_b32_e32 v72, v196
	v_mov_b32_e32 v73, v197
	ds_read_b64 v[76:77], v0 offset:8192
	s_waitcnt lgkmcnt(0)
	v_sub_f32_e32 v37, v37, v76
	v_sub_f32_e32 v36, v36, v76
	v_sub_f32_e32 v35, v35, v76
	v_sub_f32_e32 v34, v34, v76
	v_pk_mul_f32 v[34:35], v[76:77], v[34:35] op_sel:[1,0]
	v_pk_mul_f32 v[36:37], v[76:77], v[36:37] op_sel:[1,0]
	s_nop 0
	v_pk_fma_f32 v[34:35], v[66:67], v[34:35], v[70:71]
	v_pk_fma_f32 v[36:37], v[68:69], v[36:37], v[72:73]
	v_cndmask_b32_e32 v35, v211, v35, vcc
	v_cndmask_b32_e32 v37, v211, v37, vcc
	v_cndmask_b32_e32 v36, v211, v36, vcc
	v_cndmask_b32_e32 v34, v211, v34, vcc
	flat_store_dwordx4 v[162:163], v[34:37] offset:512
	s_nop 1
	v_cvt_pk_bf16_f32 v34, v34, v35
	v_cvt_pk_bf16_f32 v35, v36, v37
	flat_store_dwordx2 v[78:79], v[34:35]
	ds_read_b64 v[34:35], v0 offset:8320
	v_lshl_add_u64 v[36:37], v[164:165], 0, v[74:75]
	v_lshl_add_u64 v[76:77], v[36:37], 1, s[0:1]
	s_waitcnt lgkmcnt(0)
	v_sub_f32_e32 v37, v41, v34
	v_sub_f32_e32 v36, v40, v34
	v_sub_f32_e32 v39, v39, v34
	v_sub_f32_e32 v38, v38, v34
	v_pk_mul_f32 v[38:39], v[34:35], v[38:39] op_sel:[1,0]
	v_pk_mul_f32 v[34:35], v[34:35], v[36:37] op_sel:[1,0]
	v_pk_fma_f32 v[38:39], v[66:67], v[38:39], v[70:71]
	v_pk_fma_f32 v[34:35], v[68:69], v[34:35], v[72:73]
	s_nop 0
	v_cndmask_b32_e32 v37, v211, v35, vcc
	v_cndmask_b32_e32 v36, v211, v34, vcc
	v_cndmask_b32_e32 v35, v211, v39, vcc
	v_cndmask_b32_e32 v34, v211, v38, vcc
	flat_store_dwordx4 v[158:159], v[34:37] offset:512
	s_nop 1
	v_cvt_pk_bf16_f32 v34, v34, v35
	v_cvt_pk_bf16_f32 v35, v36, v37
	flat_store_dwordx2 v[76:77], v[34:35]
	ds_read_b64 v[34:35], v0 offset:8448
	v_lshl_add_u64 v[36:37], v[160:161], 0, v[74:75]
	v_lshl_add_u64 v[38:39], v[36:37], 1, s[0:1]
	s_waitcnt lgkmcnt(0)
	v_sub_f32_e32 v37, v45, v34
	v_sub_f32_e32 v36, v44, v34
	v_sub_f32_e32 v41, v43, v34
	v_sub_f32_e32 v40, v42, v34
	v_pk_mul_f32 v[40:41], v[34:35], v[40:41] op_sel:[1,0]
	v_pk_mul_f32 v[34:35], v[34:35], v[36:37] op_sel:[1,0]
	v_pk_fma_f32 v[40:41], v[66:67], v[40:41], v[70:71]
	v_pk_fma_f32 v[34:35], v[68:69], v[34:35], v[72:73]
	v_lshl_add_u64 v[44:45], v[154:155], 0, v[138:139]
	v_cndmask_b32_e32 v37, v211, v35, vcc
	v_cndmask_b32_e32 v36, v211, v34, vcc
	v_cndmask_b32_e32 v35, v211, v41, vcc
	v_cndmask_b32_e32 v34, v211, v40, vcc
	flat_store_dwordx4 v[140:141], v[34:37] offset:512
	v_lshl_add_u64 v[44:45], v[44:45], 1, s[0:1]
	s_nop 0
	v_cvt_pk_bf16_f32 v34, v34, v35
	v_cvt_pk_bf16_f32 v35, v36, v37
	flat_store_dwordx2 v[38:39], v[34:35]
	ds_read_b64 v[34:35], v0 offset:8576
	v_lshl_add_u64 v[36:37], v[156:157], 0, v[74:75]
	v_lshl_add_u64 v[38:39], v[36:37], 1, s[0:1]
	s_waitcnt lgkmcnt(0)
	v_sub_f32_e32 v37, v49, v34
	v_sub_f32_e32 v36, v48, v34
	v_sub_f32_e32 v41, v47, v34
	v_sub_f32_e32 v40, v46, v34
	v_pk_mul_f32 v[40:41], v[34:35], v[40:41] op_sel:[1,0]
	v_pk_mul_f32 v[34:35], v[34:35], v[36:37] op_sel:[1,0]
	v_pk_fma_f32 v[40:41], v[66:67], v[40:41], v[70:71]
	v_pk_fma_f32 v[34:35], v[68:69], v[34:35], v[72:73]
	s_nop 0
	v_cndmask_b32_e32 v37, v211, v35, vcc
	v_cndmask_b32_e32 v36, v211, v34, vcc
	v_cndmask_b32_e32 v35, v211, v41, vcc
	v_cndmask_b32_e32 v34, v211, v40, vcc
	flat_store_dwordx4 v[106:107], v[34:37] offset:512
	s_nop 1
	v_cvt_pk_bf16_f32 v34, v34, v35
	v_cvt_pk_bf16_f32 v35, v36, v37
	flat_store_dwordx2 v[38:39], v[34:35]
	ds_read_b64 v[34:35], v0 offset:9216
	v_lshl_add_u64 v[36:37], v[142:143], 0, v[74:75]
	v_lshl_add_u64 v[38:39], v[36:37], 1, s[0:1]
	s_waitcnt lgkmcnt(0)
	v_sub_f32_e32 v37, v53, v34
	v_sub_f32_e32 v36, v52, v34
	v_sub_f32_e32 v41, v51, v34
	v_sub_f32_e32 v40, v50, v34
	v_pk_mul_f32 v[40:41], v[34:35], v[40:41] op_sel:[1,0]
	v_pk_mul_f32 v[34:35], v[34:35], v[36:37] op_sel:[1,0]
	v_pk_fma_f32 v[40:41], v[66:67], v[40:41], v[70:71]
	v_pk_fma_f32 v[34:35], v[68:69], v[34:35], v[72:73]
	s_nop 0
	v_cndmask_b32_e32 v37, v211, v35, vcc
	v_cndmask_b32_e32 v36, v211, v34, vcc
	v_cndmask_b32_e32 v35, v211, v41, vcc
	v_cndmask_b32_e32 v34, v211, v40, vcc
	flat_store_dwordx4 v[108:109], v[34:37] offset:512
	s_nop 1
	v_cvt_pk_bf16_f32 v34, v34, v35
	v_cvt_pk_bf16_f32 v35, v36, v37
	flat_store_dwordx2 v[38:39], v[34:35]
	ds_read_b64 v[34:35], v0 offset:9344
	v_lshl_add_u64 v[36:37], v[144:145], 0, v[74:75]
	v_lshl_add_u64 v[38:39], v[36:37], 1, s[0:1]
	s_waitcnt lgkmcnt(0)
	v_sub_f32_e32 v37, v57, v34
	v_sub_f32_e32 v36, v56, v34
	v_sub_f32_e32 v41, v55, v34
	v_sub_f32_e32 v40, v54, v34
	v_pk_mul_f32 v[40:41], v[34:35], v[40:41] op_sel:[1,0]
	v_pk_mul_f32 v[34:35], v[34:35], v[36:37] op_sel:[1,0]
	v_pk_fma_f32 v[40:41], v[66:67], v[40:41], v[70:71]
	v_pk_fma_f32 v[34:35], v[68:69], v[34:35], v[72:73]
	s_nop 0
	v_cndmask_b32_e32 v37, v211, v35, vcc
	v_cndmask_b32_e32 v36, v211, v34, vcc
	v_cndmask_b32_e32 v35, v211, v41, vcc
	v_cndmask_b32_e32 v34, v211, v40, vcc
	flat_store_dwordx4 v[112:113], v[34:37] offset:512
	s_nop 1
	v_cvt_pk_bf16_f32 v34, v34, v35
	v_cvt_pk_bf16_f32 v35, v36, v37
	flat_store_dwordx2 v[38:39], v[34:35]
	ds_read_b64 v[34:35], v0 offset:9472
	v_lshl_add_u64 v[38:39], v[118:119], 0, v[74:75]
	s_waitcnt lgkmcnt(0)
	v_sub_f32_e32 v37, v61, v34
	v_sub_f32_e32 v36, v60, v34
	v_sub_f32_e32 v41, v59, v34
	v_sub_f32_e32 v40, v58, v34
	v_pk_mul_f32 v[40:41], v[34:35], v[40:41] op_sel:[1,0]
	v_pk_mul_f32 v[34:35], v[34:35], v[36:37] op_sel:[1,0]
	v_pk_fma_f32 v[40:41], v[66:67], v[40:41], v[70:71]
	v_pk_fma_f32 v[34:35], v[68:69], v[34:35], v[72:73]
	s_nop 0
	v_cndmask_b32_e32 v37, v211, v35, vcc
	v_cndmask_b32_e32 v36, v211, v34, vcc
	v_cndmask_b32_e32 v35, v211, v41, vcc
	v_cndmask_b32_e32 v34, v211, v40, vcc
	flat_store_dwordx4 v[110:111], v[34:37] offset:512
	s_nop 1
	v_cvt_pk_bf16_f32 v34, v34, v35
	v_cvt_pk_bf16_f32 v35, v36, v37
	v_lshl_add_u64 v[36:37], v[38:39], 1, s[0:1]
	flat_store_dwordx2 v[36:37], v[34:35]
	ds_read_b64 v[34:35], v0 offset:9600
	v_lshl_add_u64 v[38:39], v[116:117], 0, v[74:75]
	s_waitcnt lgkmcnt(0)
	v_sub_f32_e32 v37, v65, v34
	v_sub_f32_e32 v36, v64, v34
	v_sub_f32_e32 v41, v63, v34
	v_sub_f32_e32 v40, v62, v34
	v_pk_mul_f32 v[40:41], v[34:35], v[40:41] op_sel:[1,0]
	v_pk_mul_f32 v[34:35], v[34:35], v[36:37] op_sel:[1,0]
	v_pk_fma_f32 v[40:41], v[66:67], v[40:41], v[70:71]
	v_pk_fma_f32 v[34:35], v[68:69], v[34:35], v[72:73]
	s_nop 0
	v_cndmask_b32_e32 v37, v211, v35, vcc
	v_cndmask_b32_e32 v36, v211, v34, vcc
	v_cndmask_b32_e32 v35, v211, v41, vcc
	v_cndmask_b32_e32 v34, v211, v40, vcc
	flat_store_dwordx4 v[114:115], v[34:37] offset:512
	s_nop 1
	v_cvt_pk_bf16_f32 v34, v34, v35
	v_cvt_pk_bf16_f32 v35, v36, v37
	v_lshl_add_u64 v[36:37], v[38:39], 1, s[0:1]
	flat_store_dwordx2 v[36:37], v[34:35]
	s_nop 1
	v_mov_b32_e32 v34, v218
	v_mov_b32_e32 v35, v219
	v_mov_b32_e32 v36, v220
	v_mov_b32_e32 v37, v221
	s_nop 0
	s_nop 1
	v_mov_b32_e32 v38, v222
	v_mov_b32_e32 v39, v223
	v_mov_b32_e32 v40, v224
	v_mov_b32_e32 v41, v225
	ds_read_b64 v[42:43], v0 offset:8192
	s_waitcnt lgkmcnt(0)
	v_sub_f32_e32 v5, v5, v42
	v_sub_f32_e32 v4, v4, v42
	v_sub_f32_e32 v3, v3, v42
	v_sub_f32_e32 v2, v2, v42
	v_pk_mul_f32 v[2:3], v[42:43], v[2:3] op_sel:[1,0]
	v_pk_mul_f32 v[4:5], v[42:43], v[4:5] op_sel:[1,0]
	s_nop 0
	v_pk_fma_f32 v[2:3], v[34:35], v[2:3], v[38:39]
	v_pk_fma_f32 v[4:5], v[36:37], v[4:5], v[40:41]
	v_cndmask_b32_e32 v3, v211, v3, vcc
	v_cndmask_b32_e32 v5, v211, v5, vcc
	v_cndmask_b32_e32 v4, v211, v4, vcc
	v_cndmask_b32_e32 v2, v211, v2, vcc
	flat_store_dwordx4 v[162:163], v[2:5] offset:576
	s_nop 1
	v_cvt_pk_bf16_f32 v2, v2, v3
	v_cvt_pk_bf16_f32 v3, v4, v5
	flat_store_dwordx2 v[44:45], v[2:3]
	ds_read_b64 v[2:3], v0 offset:8320
	v_lshl_add_u64 v[4:5], v[164:165], 0, v[138:139]
	v_lshl_add_u64 v[42:43], v[4:5], 1, s[0:1]
	s_waitcnt lgkmcnt(0)
	v_sub_f32_e32 v5, v9, v2
	v_sub_f32_e32 v4, v8, v2
	v_sub_f32_e32 v7, v7, v2
	v_sub_f32_e32 v6, v6, v2
	v_pk_mul_f32 v[6:7], v[2:3], v[6:7] op_sel:[1,0]
	v_pk_mul_f32 v[2:3], v[2:3], v[4:5] op_sel:[1,0]
	v_pk_fma_f32 v[6:7], v[34:35], v[6:7], v[38:39]
	v_pk_fma_f32 v[2:3], v[36:37], v[2:3], v[40:41]
	s_nop 0
	v_cndmask_b32_e32 v5, v211, v3, vcc
	v_cndmask_b32_e32 v4, v211, v2, vcc
	v_cndmask_b32_e32 v3, v211, v7, vcc
	v_cndmask_b32_e32 v2, v211, v6, vcc
	flat_store_dwordx4 v[158:159], v[2:5] offset:576
	s_nop 1
	v_cvt_pk_bf16_f32 v2, v2, v3
	v_cvt_pk_bf16_f32 v3, v4, v5
	flat_store_dwordx2 v[42:43], v[2:3]
	ds_read_b64 v[2:3], v0 offset:8448
	v_lshl_add_u64 v[4:5], v[160:161], 0, v[138:139]
	v_lshl_add_u64 v[6:7], v[4:5], 1, s[0:1]
	s_waitcnt lgkmcnt(0)
	v_sub_f32_e32 v5, v13, v2
	v_sub_f32_e32 v4, v12, v2
	v_sub_f32_e32 v9, v11, v2
	v_sub_f32_e32 v8, v10, v2
	v_pk_mul_f32 v[8:9], v[2:3], v[8:9] op_sel:[1,0]
	v_pk_mul_f32 v[2:3], v[2:3], v[4:5] op_sel:[1,0]
	v_pk_fma_f32 v[8:9], v[34:35], v[8:9], v[38:39]
	v_pk_fma_f32 v[2:3], v[36:37], v[2:3], v[40:41]
	s_nop 0
	v_cndmask_b32_e32 v5, v211, v3, vcc
	v_cndmask_b32_e32 v4, v211, v2, vcc
	v_cndmask_b32_e32 v3, v211, v9, vcc
	v_cndmask_b32_e32 v2, v211, v8, vcc
	flat_store_dwordx4 v[140:141], v[2:5] offset:576
	s_nop 1
	v_cvt_pk_bf16_f32 v2, v2, v3
	v_cvt_pk_bf16_f32 v3, v4, v5
	flat_store_dwordx2 v[6:7], v[2:3]
	ds_read_b64 v[2:3], v0 offset:8576
	v_lshl_add_u64 v[4:5], v[156:157], 0, v[138:139]
	v_lshl_add_u64 v[6:7], v[4:5], 1, s[0:1]
	s_waitcnt lgkmcnt(0)
	v_sub_f32_e32 v5, v17, v2
	v_sub_f32_e32 v4, v16, v2
	v_sub_f32_e32 v9, v15, v2
	v_sub_f32_e32 v8, v14, v2
	v_pk_mul_f32 v[8:9], v[2:3], v[8:9] op_sel:[1,0]
	v_pk_mul_f32 v[2:3], v[2:3], v[4:5] op_sel:[1,0]
	v_pk_fma_f32 v[8:9], v[34:35], v[8:9], v[38:39]
	v_pk_fma_f32 v[2:3], v[36:37], v[2:3], v[40:41]
	s_nop 0
	v_cndmask_b32_e32 v5, v211, v3, vcc
	v_cndmask_b32_e32 v4, v211, v2, vcc
	v_cndmask_b32_e32 v3, v211, v9, vcc
	v_cndmask_b32_e32 v2, v211, v8, vcc
	flat_store_dwordx4 v[106:107], v[2:5] offset:576
	s_nop 1
	v_cvt_pk_bf16_f32 v2, v2, v3
	v_cvt_pk_bf16_f32 v3, v4, v5
	flat_store_dwordx2 v[6:7], v[2:3]
	ds_read_b64 v[2:3], v0 offset:9216
	v_lshl_add_u64 v[4:5], v[142:143], 0, v[138:139]
	v_lshl_add_u64 v[6:7], v[4:5], 1, s[0:1]
	s_waitcnt lgkmcnt(0)
	v_sub_f32_e32 v5, v21, v2
	v_sub_f32_e32 v4, v20, v2
	v_sub_f32_e32 v9, v19, v2
	v_sub_f32_e32 v8, v18, v2
	v_pk_mul_f32 v[8:9], v[2:3], v[8:9] op_sel:[1,0]
	v_pk_mul_f32 v[2:3], v[2:3], v[4:5] op_sel:[1,0]
	v_pk_fma_f32 v[8:9], v[34:35], v[8:9], v[38:39]
	v_pk_fma_f32 v[2:3], v[36:37], v[2:3], v[40:41]
	s_nop 0
	v_cndmask_b32_e32 v5, v211, v3, vcc
	v_cndmask_b32_e32 v4, v211, v2, vcc
	v_cndmask_b32_e32 v3, v211, v9, vcc
	v_cndmask_b32_e32 v2, v211, v8, vcc
	flat_store_dwordx4 v[108:109], v[2:5] offset:576
	s_nop 1
	v_cvt_pk_bf16_f32 v2, v2, v3
	v_cvt_pk_bf16_f32 v3, v4, v5
	flat_store_dwordx2 v[6:7], v[2:3]
	ds_read_b64 v[2:3], v0 offset:9344
	v_lshl_add_u64 v[4:5], v[144:145], 0, v[138:139]
	v_lshl_add_u64 v[6:7], v[4:5], 1, s[0:1]
	s_waitcnt lgkmcnt(0)
	v_sub_f32_e32 v5, v25, v2
	v_sub_f32_e32 v4, v24, v2
	v_sub_f32_e32 v9, v23, v2
	v_sub_f32_e32 v8, v22, v2
	v_pk_mul_f32 v[8:9], v[2:3], v[8:9] op_sel:[1,0]
	v_pk_mul_f32 v[2:3], v[2:3], v[4:5] op_sel:[1,0]
	v_pk_fma_f32 v[8:9], v[34:35], v[8:9], v[38:39]
	v_pk_fma_f32 v[2:3], v[36:37], v[2:3], v[40:41]
	s_nop 0
	v_cndmask_b32_e32 v5, v211, v3, vcc
	v_cndmask_b32_e32 v4, v211, v2, vcc
	v_cndmask_b32_e32 v3, v211, v9, vcc
	v_cndmask_b32_e32 v2, v211, v8, vcc
	flat_store_dwordx4 v[112:113], v[2:5] offset:576
	s_nop 1
	v_cvt_pk_bf16_f32 v2, v2, v3
	v_cvt_pk_bf16_f32 v3, v4, v5
	flat_store_dwordx2 v[6:7], v[2:3]
	ds_read_b64 v[2:3], v0 offset:9472
	v_lshl_add_u64 v[4:5], v[118:119], 0, v[138:139]
	v_lshl_add_u64 v[6:7], v[4:5], 1, s[0:1]
	s_waitcnt lgkmcnt(0)
	v_sub_f32_e32 v5, v29, v2
	v_sub_f32_e32 v4, v28, v2
	v_sub_f32_e32 v9, v27, v2
	v_sub_f32_e32 v8, v26, v2
	v_pk_mul_f32 v[8:9], v[2:3], v[8:9] op_sel:[1,0]
	v_pk_mul_f32 v[2:3], v[2:3], v[4:5] op_sel:[1,0]
	v_pk_fma_f32 v[8:9], v[34:35], v[8:9], v[38:39]
	v_pk_fma_f32 v[2:3], v[36:37], v[2:3], v[40:41]
	s_nop 0
	v_cndmask_b32_e32 v5, v211, v3, vcc
	v_cndmask_b32_e32 v4, v211, v2, vcc
	v_cndmask_b32_e32 v3, v211, v9, vcc
	v_cndmask_b32_e32 v2, v211, v8, vcc
	flat_store_dwordx4 v[110:111], v[2:5] offset:576
	s_nop 1
	v_cvt_pk_bf16_f32 v2, v2, v3
	v_cvt_pk_bf16_f32 v3, v4, v5
	flat_store_dwordx2 v[6:7], v[2:3]
	ds_read_b64 v[2:3], v0 offset:9600
	v_lshl_add_u64 v[6:7], v[116:117], 0, v[138:139]
	s_waitcnt lgkmcnt(0)
	v_sub_f32_e32 v5, v33, v2
	v_sub_f32_e32 v4, v32, v2
	v_sub_f32_e32 v9, v31, v2
	v_sub_f32_e32 v8, v30, v2
	v_pk_mul_f32 v[8:9], v[2:3], v[8:9] op_sel:[1,0]
	v_pk_mul_f32 v[2:3], v[2:3], v[4:5] op_sel:[1,0]
	v_pk_fma_f32 v[8:9], v[34:35], v[8:9], v[38:39]
	v_pk_fma_f32 v[2:3], v[36:37], v[2:3], v[40:41]
	s_nop 0
	v_cndmask_b32_e32 v5, v211, v3, vcc
	v_cndmask_b32_e32 v4, v211, v2, vcc
	v_cndmask_b32_e32 v3, v211, v9, vcc
	v_cndmask_b32_e32 v2, v211, v8, vcc
	flat_store_dwordx4 v[114:115], v[2:5] offset:576
	s_nop 1
	v_cvt_pk_bf16_f32 v2, v2, v3
	v_cvt_pk_bf16_f32 v3, v4, v5
	v_lshl_add_u64 v[4:5], v[6:7], 1, s[0:1]
	flat_store_dwordx2 v[4:5], v[2:3]

.LBB0_1176:
	s_add_i32 s3, s16, 0x200e8
	s_add_i32 s22, s61, 64
	s_lshl_b32 s2, s44, 5
	v_mov_b32_e32 v0, s3
	s_lshl_b32 s3, s6, 8
	ds_read_b64 v[134:135], v0
	s_or_b32 s2, s3, s2
	v_lshrrev_b32_e32 v0, 2, v150
	s_lshl_b32 s4, s22, 8
	v_and_or_b32 v138, v0, 12, s2
	v_add_u32_e32 v140, s4, v154
	v_ashrrev_i32_e32 v139, 31, v138
	v_ashrrev_i32_e32 v141, 31, v140
	v_lshl_add_u64 v[136:137], v[138:139], 2, s[0:1]
	v_lshlrev_b64 v[94:95], 12, v[140:141]
	v_lshl_add_u64 v[152:153], v[136:137], 0, v[94:95]
	v_mov_b64_e32 v[246:247], v[152:153]
	global_load_dwordx4 v[182:185], v[246:247], off
	global_load_dwordx4 v[186:189], v[246:247], off offset:64
	global_load_dwordx4 v[190:193], v[246:247], off offset:512
	global_load_dwordx4 v[194:197], v[246:247], off offset:576
	s_mov_b32 s100, 0x10000
	s_mov_b32 s101, 0
	v_lshl_add_u64 v[230:231], v[246:247], 0, s[100:101]
	global_load_dwordx4 v[234:237], v[230:231], off offset:64
	global_load_dwordx4 v[238:241], v[230:231], off offset:512
	global_load_dwordx4 v[242:245], v[230:231], off offset:576
	global_load_dwordx4 v[230:233], v[230:231], off
	v_or_b32_e32 v152, 16, v140
	v_ashrrev_i32_e32 v153, 31, v152
	v_lshlrev_b64 v[152:153], 12, v[152:153]
	s_mov_b32 s0, 0x3fb504f3
	v_lshl_add_u64 v[152:153], v[136:137], 0, v[152:153]
	v_xor_b32_e32 v0, 16, v204
	s_waitcnt lgkmcnt(0)
	v_readfirstlane_b32 s24, v134
	v_readfirstlane_b32 s23, v135
	s_waitcnt vmcnt(4) lgkmcnt(0)
	v_pk_fma_f32 v[96:97], v[184:185], s[0:1], v[4:5] op_sel_hi:[1,0,1]
	v_pk_fma_f32 v[94:95], v[182:183], s[0:1], v[2:3] op_sel_hi:[1,0,1]
	v_pk_fma_f32 v[68:69], v[188:189], s[0:1], v[68:69] op_sel_hi:[1,0,1]
	v_pk_fma_f32 v[66:67], v[186:187], s[0:1], v[66:67] op_sel_hi:[1,0,1]
	v_pk_fma_f32 v[36:37], v[192:193], s[0:1], v[36:37] op_sel_hi:[1,0,1]
	v_pk_fma_f32 v[34:35], v[190:191], s[0:1], v[34:35] op_sel_hi:[1,0,1]
	v_pk_fma_f32 v[4:5], v[196:197], s[0:1], v[132:133] op_sel_hi:[1,0,1]
	v_pk_fma_f32 v[2:3], v[194:195], s[0:1], v[130:131] op_sel_hi:[1,0,1]
	s_nop 0
	s_mov_b32 s100, 0x20000
	s_mov_b32 s101, 0
	v_lshl_add_u64 v[156:157], v[246:247], 0, s[100:101]
	global_load_dwordx4 v[160:163], v[156:157], off offset:64
	global_load_dwordx4 v[164:167], v[156:157], off offset:512
	global_load_dwordx4 v[168:171], v[156:157], off offset:576
	global_load_dwordx4 v[156:159], v[156:157], off
	s_mov_b32 s100, 0x30000
	s_mov_b32 s101, 0
	v_lshl_add_u64 v[182:183], v[246:247], 0, s[100:101]
	global_load_dwordx4 v[186:189], v[182:183], off offset:64
	global_load_dwordx4 v[190:193], v[182:183], off offset:512
	global_load_dwordx4 v[194:197], v[182:183], off offset:576
	global_load_dwordx4 v[182:185], v[182:183], off
	v_or_b32_e32 v152, 32, v140
	v_ashrrev_i32_e32 v153, 31, v152
	v_lshlrev_b64 v[152:153], 12, v[152:153]
	v_lshl_add_u64 v[152:153], v[136:137], 0, v[152:153]
	v_mov_b32_e32 v172, v94
	v_mov_b32_e32 v173, v97
	v_mov_b32_e32 v174, v67
	v_mov_b32_e32 v175, v68
	v_mov_b32_e32 v176, v5
	s_waitcnt vmcnt(8) lgkmcnt(0)
	v_pk_fma_f32 v[104:105], v[232:233], s[0:1], v[104:105] op_sel_hi:[1,0,1]
	v_pk_fma_f32 v[102:103], v[230:231], s[0:1], v[102:103] op_sel_hi:[1,0,1]
	v_pk_fma_f32 v[72:73], v[236:237], s[0:1], v[72:73] op_sel_hi:[1,0,1]
	v_pk_fma_f32 v[70:71], v[234:235], s[0:1], v[70:71] op_sel_hi:[1,0,1]
	v_pk_fma_f32 v[40:41], v[240:241], s[0:1], v[40:41] op_sel_hi:[1,0,1]
	v_pk_fma_f32 v[38:39], v[238:239], s[0:1], v[38:39] op_sel_hi:[1,0,1]
	v_pk_fma_f32 v[8:9], v[244:245], s[0:1], v[8:9] op_sel_hi:[1,0,1]
	v_pk_fma_f32 v[6:7], v[242:243], s[0:1], v[6:7] op_sel_hi:[1,0,1]
	s_nop 0
	s_mov_b32 s100, 0x80000
	s_mov_b32 s101, 0
	v_lshl_add_u64 v[230:231], v[246:247], 0, s[100:101]
	global_load_dwordx4 v[234:237], v[230:231], off offset:64
	global_load_dwordx4 v[238:241], v[230:231], off offset:512
	global_load_dwordx4 v[242:245], v[230:231], off offset:576
	global_load_dwordx4 v[230:233], v[230:231], off
	v_or_b32_e32 v152, 48, v140
	v_ashrrev_i32_e32 v153, 31, v152
	v_lshlrev_b64 v[152:153], 12, v[152:153]
	v_lshl_add_u64 v[152:153], v[136:137], 0, v[152:153]
	s_waitcnt vmcnt(8) lgkmcnt(0)
	v_pk_fma_f32 v[108:109], v[158:159], s[0:1], v[108:109] op_sel_hi:[1,0,1]
	v_pk_fma_f32 v[106:107], v[156:157], s[0:1], v[106:107] op_sel_hi:[1,0,1]
	v_pk_fma_f32 v[76:77], v[162:163], s[0:1], v[76:77] op_sel_hi:[1,0,1]
	v_pk_fma_f32 v[74:75], v[160:161], s[0:1], v[74:75] op_sel_hi:[1,0,1]
	v_pk_fma_f32 v[44:45], v[166:167], s[0:1], v[44:45] op_sel_hi:[1,0,1]
	v_pk_fma_f32 v[42:43], v[164:165], s[0:1], v[42:43] op_sel_hi:[1,0,1]
	v_pk_fma_f32 v[12:13], v[170:171], s[0:1], v[12:13] op_sel_hi:[1,0,1]
	v_pk_fma_f32 v[10:11], v[168:169], s[0:1], v[10:11] op_sel_hi:[1,0,1]
	v_add_u32_e32 v142, 0x80, v140
	s_mov_b32 s100, 0x90000
	s_mov_b32 s101, 0
	v_lshl_add_u64 v[156:157], v[246:247], 0, s[100:101]
	global_load_dwordx4 v[160:163], v[156:157], off offset:64
	global_load_dwordx4 v[164:167], v[156:157], off offset:512
	global_load_dwordx4 v[168:171], v[156:157], off offset:576
	global_load_dwordx4 v[156:159], v[156:157], off
	v_ashrrev_i32_e32 v143, 31, v142
	v_lshlrev_b64 v[148:149], 12, v[142:143]
	v_lshl_add_u64 v[152:153], v[136:137], 0, v[148:149]
	s_waitcnt vmcnt(8) lgkmcnt(0)
	v_pk_fma_f32 v[112:113], v[184:185], s[0:1], v[112:113] op_sel_hi:[1,0,1]
	v_pk_fma_f32 v[110:111], v[182:183], s[0:1], v[110:111] op_sel_hi:[1,0,1]
	v_pk_fma_f32 v[80:81], v[188:189], s[0:1], v[80:81] op_sel_hi:[1,0,1]
	v_pk_fma_f32 v[78:79], v[186:187], s[0:1], v[78:79] op_sel_hi:[1,0,1]
	v_pk_fma_f32 v[48:49], v[192:193], s[0:1], v[48:49] op_sel_hi:[1,0,1]
	v_pk_fma_f32 v[46:47], v[190:191], s[0:1], v[46:47] op_sel_hi:[1,0,1]
	v_pk_fma_f32 v[16:17], v[196:197], s[0:1], v[16:17] op_sel_hi:[1,0,1]
	v_pk_fma_f32 v[14:15], v[194:195], s[0:1], v[14:15] op_sel_hi:[1,0,1]
	v_add_u32_e32 v144, 0x90, v140
	s_mov_b32 s100, 0xa0000
	s_mov_b32 s101, 0
	v_lshl_add_u64 v[182:183], v[246:247], 0, s[100:101]
	global_load_dwordx4 v[186:189], v[182:183], off offset:64
	global_load_dwordx4 v[190:193], v[182:183], off offset:512
	global_load_dwordx4 v[194:197], v[182:183], off offset:576
	global_load_dwordx4 v[182:185], v[182:183], off
	v_ashrrev_i32_e32 v145, 31, v144
	v_lshlrev_b64 v[152:153], 12, v[144:145]
	v_lshl_add_u64 v[152:153], v[136:137], 0, v[152:153]
	s_waitcnt vmcnt(8) lgkmcnt(0)
	v_pk_fma_f32 v[116:117], v[232:233], s[0:1], v[116:117] op_sel_hi:[1,0,1]
	v_pk_fma_f32 v[114:115], v[230:231], s[0:1], v[114:115] op_sel_hi:[1,0,1]
	v_pk_fma_f32 v[84:85], v[236:237], s[0:1], v[84:85] op_sel_hi:[1,0,1]
	v_pk_fma_f32 v[82:83], v[234:235], s[0:1], v[82:83] op_sel_hi:[1,0,1]
	v_pk_fma_f32 v[52:53], v[240:241], s[0:1], v[52:53] op_sel_hi:[1,0,1]
	v_pk_fma_f32 v[50:51], v[238:239], s[0:1], v[50:51] op_sel_hi:[1,0,1]
	v_pk_fma_f32 v[20:21], v[244:245], s[0:1], v[20:21] op_sel_hi:[1,0,1]
	v_pk_fma_f32 v[18:19], v[242:243], s[0:1], v[18:19] op_sel_hi:[1,0,1]
	v_add_u32_e32 v146, 0xa0, v140
	s_mov_b32 s100, 0xb0000
	s_mov_b32 s101, 0
	v_lshl_add_u64 v[230:231], v[246:247], 0, s[100:101]
	global_load_dwordx4 v[234:237], v[230:231], off offset:64
	global_load_dwordx4 v[238:241], v[230:231], off offset:512
	global_load_dwordx4 v[242:245], v[230:231], off offset:576
	global_load_dwordx4 v[230:233], v[230:231], off
	v_ashrrev_i32_e32 v147, 31, v146
	v_lshlrev_b64 v[148:149], 12, v[146:147]
	v_lshl_add_u64 v[148:149], v[136:137], 0, v[148:149]
	s_waitcnt vmcnt(8) lgkmcnt(0)
	v_pk_fma_f32 v[120:121], v[158:159], s[0:1], v[120:121] op_sel_hi:[1,0,1]
	v_pk_fma_f32 v[118:119], v[156:157], s[0:1], v[118:119] op_sel_hi:[1,0,1]
	v_pk_fma_f32 v[88:89], v[162:163], s[0:1], v[88:89] op_sel_hi:[1,0,1]
	v_pk_fma_f32 v[86:87], v[160:161], s[0:1], v[86:87] op_sel_hi:[1,0,1]
	v_pk_fma_f32 v[56:57], v[166:167], s[0:1], v[56:57] op_sel_hi:[1,0,1]
	v_pk_fma_f32 v[54:55], v[164:165], s[0:1], v[54:55] op_sel_hi:[1,0,1]
	v_pk_fma_f32 v[24:25], v[170:171], s[0:1], v[24:25] op_sel_hi:[1,0,1]
	v_pk_fma_f32 v[22:23], v[168:169], s[0:1], v[22:23] op_sel_hi:[1,0,1]
	s_nop 0
	v_and_b32_e32 v148, 64, v204
	v_add_u32_e32 v155, 64, v148
	v_add_u32_e32 v148, 0xb0, v140
	v_ashrrev_i32_e32 v149, 31, v148
	v_lshlrev_b64 v[152:153], 12, v[148:149]
	v_lshl_add_u64 v[136:137], v[136:137], 0, v[152:153]
	v_mov_b32_e32 v152, v95
	v_mov_b32_e32 v153, v96
	v_pk_add_f32 v[152:153], v[152:153], v[172:173]
	v_cmp_lt_i32_e32 vcc, v0, v155
	s_waitcnt vmcnt(4) lgkmcnt(0)
	v_pk_fma_f32 v[124:125], v[184:185], s[0:1], v[124:125] op_sel_hi:[1,0,1]
	v_pk_fma_f32 v[122:123], v[182:183], s[0:1], v[122:123] op_sel_hi:[1,0,1]
	v_pk_fma_f32 v[92:93], v[188:189], s[0:1], v[92:93] op_sel_hi:[1,0,1]
	v_pk_fma_f32 v[90:91], v[186:187], s[0:1], v[90:91] op_sel_hi:[1,0,1]
	v_pk_fma_f32 v[60:61], v[192:193], s[0:1], v[60:61] op_sel_hi:[1,0,1]
	v_pk_fma_f32 v[58:59], v[190:191], s[0:1], v[58:59] op_sel_hi:[1,0,1]
	v_pk_fma_f32 v[28:29], v[196:197], s[0:1], v[28:29] op_sel_hi:[1,0,1]
	v_pk_fma_f32 v[26:27], v[194:195], s[0:1], v[26:27] op_sel_hi:[1,0,1]
	v_mov_b32_e32 v130, v66
	v_mov_b32_e32 v131, v69
	v_add_f32_e32 v133, v34, v35
	v_add_f32_e32 v137, v36, v37
	v_mov_b32_e32 v132, v2
	v_mov_b32_e32 v136, v3
	v_pk_add_f32 v[130:131], v[174:175], v[130:131]
	v_pk_add_f32 v[132:133], v[132:133], v[136:137]
	v_add_f32_e32 v136, v152, v153
	v_pk_add_f32 v[130:131], v[130:131], v[130:131] op_sel_hi:[0,1]
	v_add_f32_e32 v177, 0, v136
	v_mov_b32_e32 v130, v4
	v_pk_add_f32 v[130:131], v[130:131], v[176:177]
	v_cndmask_b32_e32 v0, v204, v0, vcc
	v_pk_add_f32 v[130:131], v[132:133], v[130:131]
	v_lshlrev_b32_e32 v0, 2, v0
	v_add_f32_e32 v131, v130, v131
	ds_bpermute_b32 v132, v0, v131
	v_xor_b32_e32 v130, 32, v204
	v_cmp_lt_i32_e32 vcc, v130, v155
	s_waitcnt lgkmcnt(0)
	v_add_f32_e32 v131, v131, v132
	v_cndmask_b32_e32 v130, v204, v130, vcc
	v_lshlrev_b32_e32 v130, 2, v130
	ds_bpermute_b32 v132, v130, v131
	s_waitcnt lgkmcnt(0)
	v_add_f32_e32 v131, v131, v132
	v_fmamk_f32 v133, v131, 0xbc800000, v97
	v_fmamk_f32 v137, v131, 0xbc800000, v95
	v_fmamk_f32 v153, v131, 0xbc800000, v69
	v_fmamk_f32 v172, v131, 0xbc800000, v67
	v_fmamk_f32 v132, v131, 0xbc800000, v96
	v_fmamk_f32 v136, v131, 0xbc800000, v94
	v_fmamk_f32 v152, v131, 0xbc800000, v68
	v_fmamk_f32 v155, v131, 0xbc800000, v66
	v_fmamk_f32 v174, v131, 0xbc800000, v37
	v_fmamk_f32 v176, v131, 0xbc800000, v35
	v_mul_f32_e32 v137, v137, v137
	v_mul_f32_e32 v133, v133, v133
	v_mul_f32_e32 v172, v172, v172
	v_mul_f32_e32 v153, v153, v153
	v_fmamk_f32 v173, v131, 0xbc800000, v36
	v_fmamk_f32 v175, v131, 0xbc800000, v34
	v_fmamk_f32 v178, v131, 0xbc800000, v5
	v_fmamk_f32 v183, v131, 0xbc800000, v3
	v_mul_f32_e32 v176, v176, v176
	v_mul_f32_e32 v174, v174, v174
	v_fmac_f32_e32 v137, v136, v136
	v_fmac_f32_e32 v133, v132, v132
	v_fmac_f32_e32 v172, v155, v155
	v_fmac_f32_e32 v153, v152, v152
	v_fmamk_f32 v177, v131, 0xbc800000, v4
	v_fmamk_f32 v182, v131, 0xbc800000, v2
	v_mul_f32_e32 v183, v183, v183
	v_mul_f32_e32 v178, v178, v178
	v_fmac_f32_e32 v176, v175, v175
	v_fmac_f32_e32 v174, v173, v173
	v_add_f32_e32 v132, v137, v133
	v_add_f32_e32 v133, v172, v153
	v_fmac_f32_e32 v183, v182, v182
	v_fmac_f32_e32 v178, v177, v177
	v_add_f32_e32 v136, v176, v174
	v_add_f32_e32 v132, v132, v133
	v_add_f32_e32 v137, v183, v178
	v_add_f32_e32 v132, v136, v132
	v_add_f32_e32 v133, v137, v132
	ds_bpermute_b32 v136, v0, v133
	v_and_b32_e32 v132, 63, v150
	v_cmp_gt_u32_e32 vcc, 16, v132
	s_waitcnt lgkmcnt(0)
	v_add_f32_e32 v133, v133, v136
	ds_bpermute_b32 v134, v130, v133
	s_waitcnt vmcnt(0) lgkmcnt(0)
	v_pk_fma_f32 v[128:129], v[232:233], s[0:1], v[128:129] op_sel_hi:[1,0,1]
	v_pk_fma_f32 v[126:127], v[230:231], s[0:1], v[126:127] op_sel_hi:[1,0,1]
	v_pk_fma_f32 v[100:101], v[236:237], s[0:1], v[100:101] op_sel_hi:[1,0,1]
	v_pk_fma_f32 v[98:99], v[234:235], s[0:1], v[98:99] op_sel_hi:[1,0,1]
	v_pk_fma_f32 v[64:65], v[240:241], s[0:1], v[64:65] op_sel_hi:[1,0,1]
	v_pk_fma_f32 v[62:63], v[238:239], s[0:1], v[62:63] op_sel_hi:[1,0,1]
	v_pk_fma_f32 v[32:33], v[244:245], s[0:1], v[32:33] op_sel_hi:[1,0,1]
	v_pk_fma_f32 v[30:31], v[242:243], s[0:1], v[30:31] op_sel_hi:[1,0,1]
	s_lshl_b32 s0, s44, 3
	s_add_i32 s2, s14, s0
	s_and_saveexec_b64 s[0:1], vcc
	s_cbranch_execz .LBB0_1178
	s_lshl_b32 s3, s37, 11
	s_add_i32 s3, s2, s3
	v_mul_f32_e32 v136, 0x3c800000, v131
	s_waitcnt lgkmcnt(0)
	v_add_f32_e32 v137, v133, v134
	v_lshl_add_u32 v131, v151, 5, s3
	ds_write_b64 v131, v[136:137]

.LBB0_1215:
	s_or_b64 exec, exec, s[0:1]
	s_add_i32 s0, s16, 0x200a0
	s_waitcnt lgkmcnt(0)
	s_barrier
	v_mov_b32_e32 v0, s0
	ds_read_b64 v[130:131], v0
	v_readlane_b32 s0, v252, 6
	s_lshl_b32 s44, s0, 10
	s_lshl_b64 s[0:1], s[44:45], 2
	v_lshlrev_b64 v[132:133], 2, v[138:139]
	s_waitcnt lgkmcnt(0)
	v_readfirstlane_b32 s2, v130
	v_readfirstlane_b32 s3, v131
	s_add_u32 s2, s2, s0
	s_addc_u32 s3, s3, s1
	s_add_i32 s4, s16, 0x200a8
	v_mov_b32_e32 v0, s4
	ds_read_b64 v[130:131], v0
	v_lshl_add_u64 v[150:151], s[2:3], 0, v[132:133]
	v_lshl_add_u32 v0, v154, 3, s14
	v_lshlrev_b64 v[154:155], 10, v[140:141]
	v_add_u32_e32 v158, 16, v140
	s_waitcnt lgkmcnt(0)
	v_readfirstlane_b32 s3, v130
	v_readfirstlane_b32 s2, v131
	s_add_u32 s0, s3, s0
	s_addc_u32 s1, s2, s1
	v_lshl_add_u64 v[152:153], s[0:1], 0, v[132:133]
	flat_load_dwordx4 v[130:133], v[150:151]
	flat_load_dwordx4 v[134:137], v[152:153]
	global_load_dwordx4 v[182:185], v[150:151], off offset:64
	global_load_dwordx4 v[186:189], v[152:153], off offset:64
	global_load_dwordx4 v[190:193], v[150:151], off offset:512
	global_load_dwordx4 v[194:197], v[152:153], off offset:512
	global_load_dwordx4 v[218:221], v[150:151], off offset:576
	global_load_dwordx4 v[222:225], v[152:153], off offset:576
	ds_read_b64 v[164:165], v0 offset:8192
	v_add_u32_e32 v160, 32, v140
	v_add_u32_e32 v166, 48, v140
	v_lshl_add_u64 v[140:141], v[154:155], 0, v[138:139]
	s_add_u32 s0, s24, 0x4bf0000
	s_waitcnt lgkmcnt(0)
	v_sub_f32_e32 v97, v97, v164
	v_sub_f32_e32 v96, v96, v164
	v_sub_f32_e32 v95, v95, v164
	v_sub_f32_e32 v94, v94, v164
	v_pk_mul_f32 v[94:95], v[164:165], v[94:95] op_sel:[1,0]
	v_pk_mul_f32 v[96:97], v[164:165], v[96:97] op_sel:[1,0]
	v_cmp_eq_u32_e32 vcc, 0, v156
	v_lshl_add_u64 v[162:163], v[140:141], 2, s[8:9]
	s_addc_u32 s1, s23, 0
	v_lshl_add_u64 v[140:141], v[140:141], 1, s[0:1]
	v_ashrrev_i32_e32 v159, 31, v158
	v_lshlrev_b64 v[164:165], 10, v[158:159]
	v_ashrrev_i32_e32 v161, 31, v160
	v_lshlrev_b64 v[160:161], 10, v[160:161]
	v_ashrrev_i32_e32 v167, 31, v166
	v_lshlrev_b64 v[156:157], 10, v[166:167]
	v_lshlrev_b64 v[142:143], 10, v[142:143]
	v_lshlrev_b64 v[144:145], 10, v[144:145]
	s_waitcnt vmcnt(0)
	v_pk_fma_f32 v[96:97], v[132:133], v[96:97], v[136:137]
	v_pk_fma_f32 v[94:95], v[130:131], v[94:95], v[134:135]
	v_cndmask_b32_e32 v97, v211, v97, vcc
	v_cndmask_b32_e32 v96, v211, v96, vcc
	v_cndmask_b32_e32 v95, v211, v95, vcc
	v_cndmask_b32_e32 v94, v211, v94, vcc
	flat_store_dwordx4 v[162:163], v[94:97]
	s_nop 1
	v_cvt_pk_bf16_f32 v94, v94, v95
	v_cvt_pk_bf16_f32 v95, v96, v97
	flat_store_dwordx2 v[140:141], v[94:95]
	ds_read_b64 v[94:95], v0 offset:8320
	v_lshl_add_u64 v[96:97], v[164:165], 0, v[138:139]
	v_lshl_add_u64 v[158:159], v[96:97], 2, s[8:9]
	v_lshl_add_u64 v[140:141], v[96:97], 1, s[0:1]
	s_waitcnt lgkmcnt(0)
	v_sub_f32_e32 v97, v105, v94
	v_sub_f32_e32 v96, v104, v94
	v_sub_f32_e32 v103, v103, v94
	v_sub_f32_e32 v102, v102, v94
	v_pk_mul_f32 v[102:103], v[94:95], v[102:103] op_sel:[1,0]
	v_pk_mul_f32 v[94:95], v[94:95], v[96:97] op_sel:[1,0]
	v_pk_fma_f32 v[102:103], v[130:131], v[102:103], v[134:135]
	v_pk_fma_f32 v[94:95], v[132:133], v[94:95], v[136:137]
	s_nop 0
	v_cndmask_b32_e32 v97, v211, v95, vcc
	v_cndmask_b32_e32 v96, v211, v94, vcc
	v_cndmask_b32_e32 v95, v211, v103, vcc
	v_cndmask_b32_e32 v94, v211, v102, vcc
	flat_store_dwordx4 v[158:159], v[94:97]
	s_nop 1
	v_cvt_pk_bf16_f32 v94, v94, v95
	v_cvt_pk_bf16_f32 v95, v96, v97
	flat_store_dwordx2 v[140:141], v[94:95]
	ds_read_b64 v[94:95], v0 offset:8448
	v_lshl_add_u64 v[96:97], v[160:161], 0, v[138:139]
	v_lshl_add_u64 v[140:141], v[96:97], 2, s[8:9]
	v_lshl_add_u64 v[102:103], v[96:97], 1, s[0:1]
	s_waitcnt lgkmcnt(0)
	v_sub_f32_e32 v97, v109, v94
	v_sub_f32_e32 v96, v108, v94
	v_sub_f32_e32 v105, v107, v94
	v_sub_f32_e32 v104, v106, v94
	v_pk_mul_f32 v[104:105], v[94:95], v[104:105] op_sel:[1,0]
	v_pk_mul_f32 v[94:95], v[94:95], v[96:97] op_sel:[1,0]
	v_pk_fma_f32 v[104:105], v[130:131], v[104:105], v[134:135]
	v_pk_fma_f32 v[94:95], v[132:133], v[94:95], v[136:137]
	s_nop 0
	v_cndmask_b32_e32 v97, v211, v95, vcc
	v_cndmask_b32_e32 v96, v211, v94, vcc
	v_cndmask_b32_e32 v95, v211, v105, vcc
	v_cndmask_b32_e32 v94, v211, v104, vcc
	flat_store_dwordx4 v[140:141], v[94:97]
	s_nop 1
	v_cvt_pk_bf16_f32 v94, v94, v95
	v_cvt_pk_bf16_f32 v95, v96, v97
	flat_store_dwordx2 v[102:103], v[94:95]
	ds_read_b64 v[94:95], v0 offset:8576
	v_lshl_add_u64 v[96:97], v[156:157], 0, v[138:139]
	v_lshl_add_u64 v[106:107], v[96:97], 2, s[8:9]
	v_lshl_add_u64 v[102:103], v[96:97], 1, s[0:1]
	s_waitcnt lgkmcnt(0)
	v_sub_f32_e32 v97, v113, v94
	v_sub_f32_e32 v96, v112, v94
	v_sub_f32_e32 v105, v111, v94
	v_sub_f32_e32 v104, v110, v94
	v_pk_mul_f32 v[104:105], v[94:95], v[104:105] op_sel:[1,0]
	v_pk_mul_f32 v[94:95], v[94:95], v[96:97] op_sel:[1,0]
	v_pk_fma_f32 v[104:105], v[130:131], v[104:105], v[134:135]
	v_pk_fma_f32 v[94:95], v[132:133], v[94:95], v[136:137]
	s_nop 0
	v_cndmask_b32_e32 v97, v211, v95, vcc
	v_cndmask_b32_e32 v96, v211, v94, vcc
	v_cndmask_b32_e32 v95, v211, v105, vcc
	v_cndmask_b32_e32 v94, v211, v104, vcc
	flat_store_dwordx4 v[106:107], v[94:97]
	s_nop 1
	v_cvt_pk_bf16_f32 v94, v94, v95
	v_cvt_pk_bf16_f32 v95, v96, v97
	flat_store_dwordx2 v[102:103], v[94:95]
	ds_read_b64 v[94:95], v0 offset:9216
	v_lshl_add_u64 v[96:97], v[142:143], 0, v[138:139]
	v_lshl_add_u64 v[108:109], v[96:97], 2, s[8:9]
	v_lshl_add_u64 v[102:103], v[96:97], 1, s[0:1]
	s_waitcnt lgkmcnt(0)
	v_sub_f32_e32 v97, v117, v94
	v_sub_f32_e32 v96, v116, v94
	v_sub_f32_e32 v105, v115, v94
	v_sub_f32_e32 v104, v114, v94
	v_pk_mul_f32 v[104:105], v[94:95], v[104:105] op_sel:[1,0]
	v_pk_mul_f32 v[94:95], v[94:95], v[96:97] op_sel:[1,0]
	v_pk_fma_f32 v[104:105], v[130:131], v[104:105], v[134:135]
	v_pk_fma_f32 v[94:95], v[132:133], v[94:95], v[136:137]
	v_lshlrev_b64 v[116:117], 10, v[148:149]
	v_cndmask_b32_e32 v97, v211, v95, vcc
	v_cndmask_b32_e32 v96, v211, v94, vcc
	v_cndmask_b32_e32 v95, v211, v105, vcc
	v_cndmask_b32_e32 v94, v211, v104, vcc
	flat_store_dwordx4 v[108:109], v[94:97]
	s_nop 1
	v_cvt_pk_bf16_f32 v94, v94, v95
	v_cvt_pk_bf16_f32 v95, v96, v97
	flat_store_dwordx2 v[102:103], v[94:95]
	ds_read_b64 v[94:95], v0 offset:9344
	v_lshl_add_u64 v[102:103], v[144:145], 0, v[138:139]
	v_lshl_add_u64 v[112:113], v[102:103], 2, s[8:9]
	s_waitcnt lgkmcnt(0)
	v_sub_f32_e32 v97, v121, v94
	v_sub_f32_e32 v96, v120, v94
	v_sub_f32_e32 v105, v119, v94
	v_sub_f32_e32 v104, v118, v94
	v_pk_mul_f32 v[104:105], v[94:95], v[104:105] op_sel:[1,0]
	v_pk_mul_f32 v[94:95], v[94:95], v[96:97] op_sel:[1,0]
	v_pk_fma_f32 v[104:105], v[130:131], v[104:105], v[134:135]
	v_pk_fma_f32 v[94:95], v[132:133], v[94:95], v[136:137]
	v_lshlrev_b64 v[118:119], 10, v[146:147]
	v_cndmask_b32_e32 v97, v211, v95, vcc
	v_cndmask_b32_e32 v96, v211, v94, vcc
	v_cndmask_b32_e32 v95, v211, v105, vcc
	v_cndmask_b32_e32 v94, v211, v104, vcc
	flat_store_dwordx4 v[112:113], v[94:97]
	v_or_b32_e32 v120, 16, v138
	v_mov_b32_e32 v121, v139
	v_cvt_pk_bf16_f32 v94, v94, v95
	v_cvt_pk_bf16_f32 v95, v96, v97
	v_lshl_add_u64 v[96:97], v[102:103], 1, s[0:1]
	flat_store_dwordx2 v[96:97], v[94:95]
	ds_read_b64 v[94:95], v0 offset:9472
	v_lshl_add_u64 v[102:103], v[118:119], 0, v[138:139]
	v_lshl_add_u64 v[110:111], v[102:103], 2, s[8:9]
	s_waitcnt lgkmcnt(0)
	v_sub_f32_e32 v97, v125, v94
	v_sub_f32_e32 v96, v124, v94
	v_sub_f32_e32 v105, v123, v94
	v_sub_f32_e32 v104, v122, v94
	v_pk_mul_f32 v[104:105], v[94:95], v[104:105] op_sel:[1,0]
	v_pk_mul_f32 v[94:95], v[94:95], v[96:97] op_sel:[1,0]
	v_pk_fma_f32 v[104:105], v[130:131], v[104:105], v[134:135]
	v_pk_fma_f32 v[94:95], v[132:133], v[94:95], v[136:137]
	v_lshl_add_u64 v[124:125], v[154:155], 0, v[120:121]
	v_cndmask_b32_e32 v97, v211, v95, vcc
	v_cndmask_b32_e32 v96, v211, v94, vcc
	v_cndmask_b32_e32 v95, v211, v105, vcc
	v_cndmask_b32_e32 v94, v211, v104, vcc
	flat_store_dwordx4 v[110:111], v[94:97]
	v_lshl_add_u64 v[124:125], v[124:125], 1, s[0:1]
	s_nop 0
	v_cvt_pk_bf16_f32 v94, v94, v95
	v_cvt_pk_bf16_f32 v95, v96, v97
	v_lshl_add_u64 v[96:97], v[102:103], 1, s[0:1]
	flat_store_dwordx2 v[96:97], v[94:95]
	ds_read_b64 v[94:95], v0 offset:9600
	v_lshl_add_u64 v[102:103], v[116:117], 0, v[138:139]
	v_lshl_add_u64 v[114:115], v[102:103], 2, s[8:9]
	s_waitcnt lgkmcnt(0)
	v_sub_f32_e32 v97, v129, v94
	v_sub_f32_e32 v96, v128, v94
	v_sub_f32_e32 v105, v127, v94
	v_sub_f32_e32 v104, v126, v94
	v_pk_mul_f32 v[104:105], v[94:95], v[104:105] op_sel:[1,0]
	v_pk_mul_f32 v[94:95], v[94:95], v[96:97] op_sel:[1,0]
	v_pk_fma_f32 v[104:105], v[130:131], v[104:105], v[134:135]
	v_pk_fma_f32 v[94:95], v[132:133], v[94:95], v[136:137]
	s_nop 0
	v_cndmask_b32_e32 v97, v211, v95, vcc
	v_cndmask_b32_e32 v96, v211, v94, vcc
	v_cndmask_b32_e32 v95, v211, v105, vcc
	v_cndmask_b32_e32 v94, v211, v104, vcc
	flat_store_dwordx4 v[114:115], v[94:97]
	s_nop 1
	v_cvt_pk_bf16_f32 v94, v94, v95
	v_cvt_pk_bf16_f32 v95, v96, v97
	v_lshl_add_u64 v[96:97], v[102:103], 1, s[0:1]
	flat_store_dwordx2 v[96:97], v[94:95]
	s_nop 1
	v_mov_b32_e32 v94, v182
	v_mov_b32_e32 v95, v183
	v_mov_b32_e32 v96, v184
	v_mov_b32_e32 v97, v185
	s_nop 0
	s_nop 1
	v_mov_b32_e32 v102, v186
	v_mov_b32_e32 v103, v187
	v_mov_b32_e32 v104, v188
	v_mov_b32_e32 v105, v189
	ds_read_b64 v[122:123], v0 offset:8192
	s_waitcnt lgkmcnt(0)
	v_sub_f32_e32 v69, v69, v122
	v_sub_f32_e32 v68, v68, v122
	v_sub_f32_e32 v67, v67, v122
	v_sub_f32_e32 v66, v66, v122
	v_pk_mul_f32 v[66:67], v[122:123], v[66:67] op_sel:[1,0]
	v_pk_mul_f32 v[68:69], v[122:123], v[68:69] op_sel:[1,0]
	s_nop 0
	v_pk_fma_f32 v[66:67], v[94:95], v[66:67], v[102:103]
	v_pk_fma_f32 v[68:69], v[96:97], v[68:69], v[104:105]
	v_cndmask_b32_e32 v67, v211, v67, vcc
	v_cndmask_b32_e32 v69, v211, v69, vcc
	v_cndmask_b32_e32 v68, v211, v68, vcc
	v_cndmask_b32_e32 v66, v211, v66, vcc
	flat_store_dwordx4 v[162:163], v[66:69] offset:64
	s_nop 1
	v_cvt_pk_bf16_f32 v66, v66, v67
	v_cvt_pk_bf16_f32 v67, v68, v69
	flat_store_dwordx2 v[124:125], v[66:67]
	ds_read_b64 v[66:67], v0 offset:8320
	v_lshl_add_u64 v[68:69], v[164:165], 0, v[120:121]
	v_lshl_add_u64 v[122:123], v[68:69], 1, s[0:1]
	s_waitcnt lgkmcnt(0)
	v_sub_f32_e32 v69, v73, v66
	v_sub_f32_e32 v68, v72, v66
	v_sub_f32_e32 v71, v71, v66
	v_sub_f32_e32 v70, v70, v66
	v_pk_mul_f32 v[70:71], v[66:67], v[70:71] op_sel:[1,0]
	v_pk_mul_f32 v[66:67], v[66:67], v[68:69] op_sel:[1,0]
	v_pk_fma_f32 v[70:71], v[94:95], v[70:71], v[102:103]
	v_pk_fma_f32 v[66:67], v[96:97], v[66:67], v[104:105]
	s_nop 0
	v_cndmask_b32_e32 v69, v211, v67, vcc
	v_cndmask_b32_e32 v68, v211, v66, vcc
	v_cndmask_b32_e32 v67, v211, v71, vcc
	v_cndmask_b32_e32 v66, v211, v70, vcc
	flat_store_dwordx4 v[158:159], v[66:69] offset:64
	s_nop 1
	v_cvt_pk_bf16_f32 v66, v66, v67
	v_cvt_pk_bf16_f32 v67, v68, v69
	flat_store_dwordx2 v[122:123], v[66:67]
	ds_read_b64 v[66:67], v0 offset:8448
	v_lshl_add_u64 v[68:69], v[160:161], 0, v[120:121]
	v_lshl_add_u64 v[70:71], v[68:69], 1, s[0:1]
	s_waitcnt lgkmcnt(0)
	v_sub_f32_e32 v69, v77, v66
	v_sub_f32_e32 v68, v76, v66
	v_sub_f32_e32 v73, v75, v66
	v_sub_f32_e32 v72, v74, v66
	v_pk_mul_f32 v[72:73], v[66:67], v[72:73] op_sel:[1,0]
	v_pk_mul_f32 v[66:67], v[66:67], v[68:69] op_sel:[1,0]
	v_pk_fma_f32 v[72:73], v[94:95], v[72:73], v[102:103]
	v_pk_fma_f32 v[66:67], v[96:97], v[66:67], v[104:105]
	v_or_b32_e32 v74, 0x80, v138
	v_cndmask_b32_e32 v69, v211, v67, vcc
	v_cndmask_b32_e32 v68, v211, v66, vcc
	v_cndmask_b32_e32 v67, v211, v73, vcc
	v_cndmask_b32_e32 v66, v211, v72, vcc
	flat_store_dwordx4 v[140:141], v[66:69] offset:64
	v_mov_b32_e32 v75, v139
	v_or_b32_e32 v138, 0x90, v138
	v_cvt_pk_bf16_f32 v66, v66, v67
	v_cvt_pk_bf16_f32 v67, v68, v69
	flat_store_dwordx2 v[70:71], v[66:67]
	ds_read_b64 v[66:67], v0 offset:8576
	v_lshl_add_u64 v[68:69], v[156:157], 0, v[120:121]
	v_lshl_add_u64 v[70:71], v[68:69], 1, s[0:1]
	s_waitcnt lgkmcnt(0)
	v_sub_f32_e32 v69, v81, v66
	v_sub_f32_e32 v68, v80, v66
	v_sub_f32_e32 v73, v79, v66
	v_sub_f32_e32 v72, v78, v66
	v_pk_mul_f32 v[72:73], v[66:67], v[72:73] op_sel:[1,0]
	v_pk_mul_f32 v[66:67], v[66:67], v[68:69] op_sel:[1,0]
	v_pk_fma_f32 v[72:73], v[94:95], v[72:73], v[102:103]
	v_pk_fma_f32 v[66:67], v[96:97], v[66:67], v[104:105]
	v_lshl_add_u64 v[78:79], v[154:155], 0, v[74:75]
	v_cndmask_b32_e32 v69, v211, v67, vcc
	v_cndmask_b32_e32 v68, v211, v66, vcc
	v_cndmask_b32_e32 v67, v211, v73, vcc
	v_cndmask_b32_e32 v66, v211, v72, vcc
	flat_store_dwordx4 v[106:107], v[66:69] offset:64
	v_lshl_add_u64 v[78:79], v[78:79], 1, s[0:1]
	s_nop 0
	v_cvt_pk_bf16_f32 v66, v66, v67
	v_cvt_pk_bf16_f32 v67, v68, v69
	flat_store_dwordx2 v[70:71], v[66:67]
	ds_read_b64 v[66:67], v0 offset:9216
	v_lshl_add_u64 v[68:69], v[142:143], 0, v[120:121]
	v_lshl_add_u64 v[70:71], v[68:69], 1, s[0:1]
	s_waitcnt lgkmcnt(0)
	v_sub_f32_e32 v69, v85, v66
	v_sub_f32_e32 v68, v84, v66
	v_sub_f32_e32 v73, v83, v66
	v_sub_f32_e32 v72, v82, v66
	v_pk_mul_f32 v[72:73], v[66:67], v[72:73] op_sel:[1,0]
	v_pk_mul_f32 v[66:67], v[66:67], v[68:69] op_sel:[1,0]
	v_pk_fma_f32 v[72:73], v[94:95], v[72:73], v[102:103]
	v_pk_fma_f32 v[66:67], v[96:97], v[66:67], v[104:105]
	s_nop 0
	v_cndmask_b32_e32 v69, v211, v67, vcc
	v_cndmask_b32_e32 v68, v211, v66, vcc
	v_cndmask_b32_e32 v67, v211, v73, vcc
	v_cndmask_b32_e32 v66, v211, v72, vcc
	flat_store_dwordx4 v[108:109], v[66:69] offset:64
	s_nop 1
	v_cvt_pk_bf16_f32 v66, v66, v67
	v_cvt_pk_bf16_f32 v67, v68, v69
	flat_store_dwordx2 v[70:71], v[66:67]
	ds_read_b64 v[66:67], v0 offset:9344
	v_lshl_add_u64 v[68:69], v[144:145], 0, v[120:121]
	v_lshl_add_u64 v[70:71], v[68:69], 1, s[0:1]
	s_waitcnt lgkmcnt(0)
	v_sub_f32_e32 v69, v89, v66
	v_sub_f32_e32 v68, v88, v66
	v_sub_f32_e32 v73, v87, v66
	v_sub_f32_e32 v72, v86, v66
	v_pk_mul_f32 v[72:73], v[66:67], v[72:73] op_sel:[1,0]
	v_pk_mul_f32 v[66:67], v[66:67], v[68:69] op_sel:[1,0]
	v_pk_fma_f32 v[72:73], v[94:95], v[72:73], v[102:103]
	v_pk_fma_f32 v[66:67], v[96:97], v[66:67], v[104:105]
	s_nop 0
	v_cndmask_b32_e32 v69, v211, v67, vcc
	v_cndmask_b32_e32 v68, v211, v66, vcc
	v_cndmask_b32_e32 v67, v211, v73, vcc
	v_cndmask_b32_e32 v66, v211, v72, vcc
	flat_store_dwordx4 v[112:113], v[66:69] offset:64
	s_nop 1
	v_cvt_pk_bf16_f32 v66, v66, v67
	v_cvt_pk_bf16_f32 v67, v68, v69
	flat_store_dwordx2 v[70:71], v[66:67]
	ds_read_b64 v[66:67], v0 offset:9472
	v_lshl_add_u64 v[70:71], v[118:119], 0, v[120:121]
	s_waitcnt lgkmcnt(0)
	v_sub_f32_e32 v69, v93, v66
	v_sub_f32_e32 v68, v92, v66
	v_sub_f32_e32 v73, v91, v66
	v_sub_f32_e32 v72, v90, v66
	v_pk_mul_f32 v[72:73], v[66:67], v[72:73] op_sel:[1,0]
	v_pk_mul_f32 v[66:67], v[66:67], v[68:69] op_sel:[1,0]
	v_pk_fma_f32 v[72:73], v[94:95], v[72:73], v[102:103]
	v_pk_fma_f32 v[66:67], v[96:97], v[66:67], v[104:105]
	s_nop 0
	v_cndmask_b32_e32 v69, v211, v67, vcc
	v_cndmask_b32_e32 v68, v211, v66, vcc
	v_cndmask_b32_e32 v67, v211, v73, vcc
	v_cndmask_b32_e32 v66, v211, v72, vcc
	flat_store_dwordx4 v[110:111], v[66:69] offset:64
	s_nop 1
	v_cvt_pk_bf16_f32 v66, v66, v67
	v_cvt_pk_bf16_f32 v67, v68, v69
	v_lshl_add_u64 v[68:69], v[70:71], 1, s[0:1]
	flat_store_dwordx2 v[68:69], v[66:67]
	ds_read_b64 v[66:67], v0 offset:9600
	v_lshl_add_u64 v[70:71], v[116:117], 0, v[120:121]
	s_waitcnt lgkmcnt(0)
	v_sub_f32_e32 v69, v101, v66
	v_sub_f32_e32 v68, v100, v66
	v_sub_f32_e32 v73, v99, v66
	v_sub_f32_e32 v72, v98, v66
	v_pk_mul_f32 v[72:73], v[66:67], v[72:73] op_sel:[1,0]
	v_pk_mul_f32 v[66:67], v[66:67], v[68:69] op_sel:[1,0]
	v_pk_fma_f32 v[72:73], v[94:95], v[72:73], v[102:103]
	v_pk_fma_f32 v[66:67], v[96:97], v[66:67], v[104:105]
	s_nop 0
	v_cndmask_b32_e32 v69, v211, v67, vcc
	v_cndmask_b32_e32 v68, v211, v66, vcc
	v_cndmask_b32_e32 v67, v211, v73, vcc
	v_cndmask_b32_e32 v66, v211, v72, vcc
	flat_store_dwordx4 v[114:115], v[66:69] offset:64
	s_nop 1
	v_cvt_pk_bf16_f32 v66, v66, v67
	v_cvt_pk_bf16_f32 v67, v68, v69
	v_lshl_add_u64 v[68:69], v[70:71], 1, s[0:1]
	flat_store_dwordx2 v[68:69], v[66:67]
	s_nop 1
	v_mov_b32_e32 v66, v190
	v_mov_b32_e32 v67, v191
	v_mov_b32_e32 v68, v192
	v_mov_b32_e32 v69, v193
	s_nop 0
	s_nop 1
	v_mov_b32_e32 v70, v194
	v_mov_b32_e32 v71, v195
	v_mov_b32_e32 v72, v196
	v_mov_b32_e32 v73, v197
	ds_read_b64 v[76:77], v0 offset:8192
	s_waitcnt lgkmcnt(0)
	v_sub_f32_e32 v37, v37, v76
	v_sub_f32_e32 v36, v36, v76
	v_sub_f32_e32 v35, v35, v76
	v_sub_f32_e32 v34, v34, v76
	v_pk_mul_f32 v[34:35], v[76:77], v[34:35] op_sel:[1,0]
	v_pk_mul_f32 v[36:37], v[76:77], v[36:37] op_sel:[1,0]
	s_nop 0
	v_pk_fma_f32 v[34:35], v[66:67], v[34:35], v[70:71]
	v_pk_fma_f32 v[36:37], v[68:69], v[36:37], v[72:73]
	v_cndmask_b32_e32 v35, v211, v35, vcc
	v_cndmask_b32_e32 v37, v211, v37, vcc
	v_cndmask_b32_e32 v36, v211, v36, vcc
	v_cndmask_b32_e32 v34, v211, v34, vcc
	flat_store_dwordx4 v[162:163], v[34:37] offset:512
	s_nop 1
	v_cvt_pk_bf16_f32 v34, v34, v35
	v_cvt_pk_bf16_f32 v35, v36, v37
	flat_store_dwordx2 v[78:79], v[34:35]
	ds_read_b64 v[34:35], v0 offset:8320
	v_lshl_add_u64 v[36:37], v[164:165], 0, v[74:75]
	v_lshl_add_u64 v[76:77], v[36:37], 1, s[0:1]
	s_waitcnt lgkmcnt(0)
	v_sub_f32_e32 v37, v41, v34
	v_sub_f32_e32 v36, v40, v34
	v_sub_f32_e32 v39, v39, v34
	v_sub_f32_e32 v38, v38, v34
	v_pk_mul_f32 v[38:39], v[34:35], v[38:39] op_sel:[1,0]
	v_pk_mul_f32 v[34:35], v[34:35], v[36:37] op_sel:[1,0]
	v_pk_fma_f32 v[38:39], v[66:67], v[38:39], v[70:71]
	v_pk_fma_f32 v[34:35], v[68:69], v[34:35], v[72:73]
	s_nop 0
	v_cndmask_b32_e32 v37, v211, v35, vcc
	v_cndmask_b32_e32 v36, v211, v34, vcc
	v_cndmask_b32_e32 v35, v211, v39, vcc
	v_cndmask_b32_e32 v34, v211, v38, vcc
	flat_store_dwordx4 v[158:159], v[34:37] offset:512
	s_nop 1
	v_cvt_pk_bf16_f32 v34, v34, v35
	v_cvt_pk_bf16_f32 v35, v36, v37
	flat_store_dwordx2 v[76:77], v[34:35]
	ds_read_b64 v[34:35], v0 offset:8448
	v_lshl_add_u64 v[36:37], v[160:161], 0, v[74:75]
	v_lshl_add_u64 v[38:39], v[36:37], 1, s[0:1]
	s_waitcnt lgkmcnt(0)
	v_sub_f32_e32 v37, v45, v34
	v_sub_f32_e32 v36, v44, v34
	v_sub_f32_e32 v41, v43, v34
	v_sub_f32_e32 v40, v42, v34
	v_pk_mul_f32 v[40:41], v[34:35], v[40:41] op_sel:[1,0]
	v_pk_mul_f32 v[34:35], v[34:35], v[36:37] op_sel:[1,0]
	v_pk_fma_f32 v[40:41], v[66:67], v[40:41], v[70:71]
	v_pk_fma_f32 v[34:35], v[68:69], v[34:35], v[72:73]
	v_lshl_add_u64 v[44:45], v[154:155], 0, v[138:139]
	v_cndmask_b32_e32 v37, v211, v35, vcc
	v_cndmask_b32_e32 v36, v211, v34, vcc
	v_cndmask_b32_e32 v35, v211, v41, vcc
	v_cndmask_b32_e32 v34, v211, v40, vcc
	flat_store_dwordx4 v[140:141], v[34:37] offset:512
	v_lshl_add_u64 v[44:45], v[44:45], 1, s[0:1]
	s_nop 0
	v_cvt_pk_bf16_f32 v34, v34, v35
	v_cvt_pk_bf16_f32 v35, v36, v37
	flat_store_dwordx2 v[38:39], v[34:35]
	ds_read_b64 v[34:35], v0 offset:8576
	v_lshl_add_u64 v[36:37], v[156:157], 0, v[74:75]
	v_lshl_add_u64 v[38:39], v[36:37], 1, s[0:1]
	s_waitcnt lgkmcnt(0)
	v_sub_f32_e32 v37, v49, v34
	v_sub_f32_e32 v36, v48, v34
	v_sub_f32_e32 v41, v47, v34
	v_sub_f32_e32 v40, v46, v34
	v_pk_mul_f32 v[40:41], v[34:35], v[40:41] op_sel:[1,0]
	v_pk_mul_f32 v[34:35], v[34:35], v[36:37] op_sel:[1,0]
	v_pk_fma_f32 v[40:41], v[66:67], v[40:41], v[70:71]
	v_pk_fma_f32 v[34:35], v[68:69], v[34:35], v[72:73]
	s_nop 0
	v_cndmask_b32_e32 v37, v211, v35, vcc
	v_cndmask_b32_e32 v36, v211, v34, vcc
	v_cndmask_b32_e32 v35, v211, v41, vcc
	v_cndmask_b32_e32 v34, v211, v40, vcc
	flat_store_dwordx4 v[106:107], v[34:37] offset:512
	s_nop 1
	v_cvt_pk_bf16_f32 v34, v34, v35
	v_cvt_pk_bf16_f32 v35, v36, v37
	flat_store_dwordx2 v[38:39], v[34:35]
	ds_read_b64 v[34:35], v0 offset:9216
	v_lshl_add_u64 v[36:37], v[142:143], 0, v[74:75]
	v_lshl_add_u64 v[38:39], v[36:37], 1, s[0:1]
	s_waitcnt lgkmcnt(0)
	v_sub_f32_e32 v37, v53, v34
	v_sub_f32_e32 v36, v52, v34
	v_sub_f32_e32 v41, v51, v34
	v_sub_f32_e32 v40, v50, v34
	v_pk_mul_f32 v[40:41], v[34:35], v[40:41] op_sel:[1,0]
	v_pk_mul_f32 v[34:35], v[34:35], v[36:37] op_sel:[1,0]
	v_pk_fma_f32 v[40:41], v[66:67], v[40:41], v[70:71]
	v_pk_fma_f32 v[34:35], v[68:69], v[34:35], v[72:73]
	s_nop 0
	v_cndmask_b32_e32 v37, v211, v35, vcc
	v_cndmask_b32_e32 v36, v211, v34, vcc
	v_cndmask_b32_e32 v35, v211, v41, vcc
	v_cndmask_b32_e32 v34, v211, v40, vcc
	flat_store_dwordx4 v[108:109], v[34:37] offset:512
	s_nop 1
	v_cvt_pk_bf16_f32 v34, v34, v35
	v_cvt_pk_bf16_f32 v35, v36, v37
	flat_store_dwordx2 v[38:39], v[34:35]
	ds_read_b64 v[34:35], v0 offset:9344
	v_lshl_add_u64 v[36:37], v[144:145], 0, v[74:75]
	v_lshl_add_u64 v[38:39], v[36:37], 1, s[0:1]
	s_waitcnt lgkmcnt(0)
	v_sub_f32_e32 v37, v57, v34
	v_sub_f32_e32 v36, v56, v34
	v_sub_f32_e32 v41, v55, v34
	v_sub_f32_e32 v40, v54, v34
	v_pk_mul_f32 v[40:41], v[34:35], v[40:41] op_sel:[1,0]
	v_pk_mul_f32 v[34:35], v[34:35], v[36:37] op_sel:[1,0]
	v_pk_fma_f32 v[40:41], v[66:67], v[40:41], v[70:71]
	v_pk_fma_f32 v[34:35], v[68:69], v[34:35], v[72:73]
	s_nop 0
	v_cndmask_b32_e32 v37, v211, v35, vcc
	v_cndmask_b32_e32 v36, v211, v34, vcc
	v_cndmask_b32_e32 v35, v211, v41, vcc
	v_cndmask_b32_e32 v34, v211, v40, vcc
	flat_store_dwordx4 v[112:113], v[34:37] offset:512
	s_nop 1
	v_cvt_pk_bf16_f32 v34, v34, v35
	v_cvt_pk_bf16_f32 v35, v36, v37
	flat_store_dwordx2 v[38:39], v[34:35]
	ds_read_b64 v[34:35], v0 offset:9472
	v_lshl_add_u64 v[38:39], v[118:119], 0, v[74:75]
	s_waitcnt lgkmcnt(0)
	v_sub_f32_e32 v37, v61, v34
	v_sub_f32_e32 v36, v60, v34
	v_sub_f32_e32 v41, v59, v34
	v_sub_f32_e32 v40, v58, v34
	v_pk_mul_f32 v[40:41], v[34:35], v[40:41] op_sel:[1,0]
	v_pk_mul_f32 v[34:35], v[34:35], v[36:37] op_sel:[1,0]
	v_pk_fma_f32 v[40:41], v[66:67], v[40:41], v[70:71]
	v_pk_fma_f32 v[34:35], v[68:69], v[34:35], v[72:73]
	s_nop 0
	v_cndmask_b32_e32 v37, v211, v35, vcc
	v_cndmask_b32_e32 v36, v211, v34, vcc
	v_cndmask_b32_e32 v35, v211, v41, vcc
	v_cndmask_b32_e32 v34, v211, v40, vcc
	flat_store_dwordx4 v[110:111], v[34:37] offset:512
	s_nop 1
	v_cvt_pk_bf16_f32 v34, v34, v35
	v_cvt_pk_bf16_f32 v35, v36, v37
	v_lshl_add_u64 v[36:37], v[38:39], 1, s[0:1]
	flat_store_dwordx2 v[36:37], v[34:35]
	ds_read_b64 v[34:35], v0 offset:9600
	v_lshl_add_u64 v[38:39], v[116:117], 0, v[74:75]
	s_waitcnt lgkmcnt(0)
	v_sub_f32_e32 v37, v65, v34
	v_sub_f32_e32 v36, v64, v34
	v_sub_f32_e32 v41, v63, v34
	v_sub_f32_e32 v40, v62, v34
	v_pk_mul_f32 v[40:41], v[34:35], v[40:41] op_sel:[1,0]
	v_pk_mul_f32 v[34:35], v[34:35], v[36:37] op_sel:[1,0]
	v_pk_fma_f32 v[40:41], v[66:67], v[40:41], v[70:71]
	v_pk_fma_f32 v[34:35], v[68:69], v[34:35], v[72:73]
	s_nop 0
	v_cndmask_b32_e32 v37, v211, v35, vcc
	v_cndmask_b32_e32 v36, v211, v34, vcc
	v_cndmask_b32_e32 v35, v211, v41, vcc
	v_cndmask_b32_e32 v34, v211, v40, vcc
	flat_store_dwordx4 v[114:115], v[34:37] offset:512
	s_nop 1
	v_cvt_pk_bf16_f32 v34, v34, v35
	v_cvt_pk_bf16_f32 v35, v36, v37
	v_lshl_add_u64 v[36:37], v[38:39], 1, s[0:1]
	flat_store_dwordx2 v[36:37], v[34:35]
	s_nop 1
	v_mov_b32_e32 v34, v218
	v_mov_b32_e32 v35, v219
	v_mov_b32_e32 v36, v220
	v_mov_b32_e32 v37, v221
	s_nop 0
	s_nop 1
	v_mov_b32_e32 v38, v222
	v_mov_b32_e32 v39, v223
	v_mov_b32_e32 v40, v224
	v_mov_b32_e32 v41, v225
	ds_read_b64 v[42:43], v0 offset:8192
	s_waitcnt lgkmcnt(0)
	v_sub_f32_e32 v5, v5, v42
	v_sub_f32_e32 v4, v4, v42
	v_sub_f32_e32 v3, v3, v42
	v_sub_f32_e32 v2, v2, v42
	v_pk_mul_f32 v[2:3], v[42:43], v[2:3] op_sel:[1,0]
	v_pk_mul_f32 v[4:5], v[42:43], v[4:5] op_sel:[1,0]
	s_nop 0
	v_pk_fma_f32 v[2:3], v[34:35], v[2:3], v[38:39]
	v_pk_fma_f32 v[4:5], v[36:37], v[4:5], v[40:41]
	v_cndmask_b32_e32 v3, v211, v3, vcc
	v_cndmask_b32_e32 v5, v211, v5, vcc
	v_cndmask_b32_e32 v4, v211, v4, vcc
	v_cndmask_b32_e32 v2, v211, v2, vcc
	flat_store_dwordx4 v[162:163], v[2:5] offset:576
	s_nop 1
	v_cvt_pk_bf16_f32 v2, v2, v3
	v_cvt_pk_bf16_f32 v3, v4, v5
	flat_store_dwordx2 v[44:45], v[2:3]
	ds_read_b64 v[2:3], v0 offset:8320
	v_lshl_add_u64 v[4:5], v[164:165], 0, v[138:139]
	v_lshl_add_u64 v[42:43], v[4:5], 1, s[0:1]
	s_waitcnt lgkmcnt(0)
	v_sub_f32_e32 v5, v9, v2
	v_sub_f32_e32 v4, v8, v2
	v_sub_f32_e32 v7, v7, v2
	v_sub_f32_e32 v6, v6, v2
	v_pk_mul_f32 v[6:7], v[2:3], v[6:7] op_sel:[1,0]
	v_pk_mul_f32 v[2:3], v[2:3], v[4:5] op_sel:[1,0]
	v_pk_fma_f32 v[6:7], v[34:35], v[6:7], v[38:39]
	v_pk_fma_f32 v[2:3], v[36:37], v[2:3], v[40:41]
	s_nop 0
	v_cndmask_b32_e32 v5, v211, v3, vcc
	v_cndmask_b32_e32 v4, v211, v2, vcc
	v_cndmask_b32_e32 v3, v211, v7, vcc
	v_cndmask_b32_e32 v2, v211, v6, vcc
	flat_store_dwordx4 v[158:159], v[2:5] offset:576
	s_nop 1
	v_cvt_pk_bf16_f32 v2, v2, v3
	v_cvt_pk_bf16_f32 v3, v4, v5
	flat_store_dwordx2 v[42:43], v[2:3]
	ds_read_b64 v[2:3], v0 offset:8448
	v_lshl_add_u64 v[4:5], v[160:161], 0, v[138:139]
	v_lshl_add_u64 v[6:7], v[4:5], 1, s[0:1]
	s_waitcnt lgkmcnt(0)
	v_sub_f32_e32 v5, v13, v2
	v_sub_f32_e32 v4, v12, v2
	v_sub_f32_e32 v9, v11, v2
	v_sub_f32_e32 v8, v10, v2
	v_pk_mul_f32 v[8:9], v[2:3], v[8:9] op_sel:[1,0]
	v_pk_mul_f32 v[2:3], v[2:3], v[4:5] op_sel:[1,0]
	v_pk_fma_f32 v[8:9], v[34:35], v[8:9], v[38:39]
	v_pk_fma_f32 v[2:3], v[36:37], v[2:3], v[40:41]
	s_nop 0
	v_cndmask_b32_e32 v5, v211, v3, vcc
	v_cndmask_b32_e32 v4, v211, v2, vcc
	v_cndmask_b32_e32 v3, v211, v9, vcc
	v_cndmask_b32_e32 v2, v211, v8, vcc
	flat_store_dwordx4 v[140:141], v[2:5] offset:576
	s_nop 1
	v_cvt_pk_bf16_f32 v2, v2, v3
	v_cvt_pk_bf16_f32 v3, v4, v5
	flat_store_dwordx2 v[6:7], v[2:3]
	ds_read_b64 v[2:3], v0 offset:8576
	v_lshl_add_u64 v[4:5], v[156:157], 0, v[138:139]
	v_lshl_add_u64 v[6:7], v[4:5], 1, s[0:1]
	s_waitcnt lgkmcnt(0)
	v_sub_f32_e32 v5, v17, v2
	v_sub_f32_e32 v4, v16, v2
	v_sub_f32_e32 v9, v15, v2
	v_sub_f32_e32 v8, v14, v2
	v_pk_mul_f32 v[8:9], v[2:3], v[8:9] op_sel:[1,0]
	v_pk_mul_f32 v[2:3], v[2:3], v[4:5] op_sel:[1,0]
	v_pk_fma_f32 v[8:9], v[34:35], v[8:9], v[38:39]
	v_pk_fma_f32 v[2:3], v[36:37], v[2:3], v[40:41]
	s_nop 0
	v_cndmask_b32_e32 v5, v211, v3, vcc
	v_cndmask_b32_e32 v4, v211, v2, vcc
	v_cndmask_b32_e32 v3, v211, v9, vcc
	v_cndmask_b32_e32 v2, v211, v8, vcc
	flat_store_dwordx4 v[106:107], v[2:5] offset:576
	s_nop 1
	v_cvt_pk_bf16_f32 v2, v2, v3
	v_cvt_pk_bf16_f32 v3, v4, v5
	flat_store_dwordx2 v[6:7], v[2:3]
	ds_read_b64 v[2:3], v0 offset:9216
	v_lshl_add_u64 v[4:5], v[142:143], 0, v[138:139]
	v_lshl_add_u64 v[6:7], v[4:5], 1, s[0:1]
	s_waitcnt lgkmcnt(0)
	v_sub_f32_e32 v5, v21, v2
	v_sub_f32_e32 v4, v20, v2
	v_sub_f32_e32 v9, v19, v2
	v_sub_f32_e32 v8, v18, v2
	v_pk_mul_f32 v[8:9], v[2:3], v[8:9] op_sel:[1,0]
	v_pk_mul_f32 v[2:3], v[2:3], v[4:5] op_sel:[1,0]
	v_pk_fma_f32 v[8:9], v[34:35], v[8:9], v[38:39]
	v_pk_fma_f32 v[2:3], v[36:37], v[2:3], v[40:41]
	s_nop 0
	v_cndmask_b32_e32 v5, v211, v3, vcc
	v_cndmask_b32_e32 v4, v211, v2, vcc
	v_cndmask_b32_e32 v3, v211, v9, vcc
	v_cndmask_b32_e32 v2, v211, v8, vcc
	flat_store_dwordx4 v[108:109], v[2:5] offset:576
	s_nop 1
	v_cvt_pk_bf16_f32 v2, v2, v3
	v_cvt_pk_bf16_f32 v3, v4, v5
	flat_store_dwordx2 v[6:7], v[2:3]
	ds_read_b64 v[2:3], v0 offset:9344
	v_lshl_add_u64 v[4:5], v[144:145], 0, v[138:139]
	v_lshl_add_u64 v[6:7], v[4:5], 1, s[0:1]
	s_waitcnt lgkmcnt(0)
	v_sub_f32_e32 v5, v25, v2
	v_sub_f32_e32 v4, v24, v2
	v_sub_f32_e32 v9, v23, v2
	v_sub_f32_e32 v8, v22, v2
	v_pk_mul_f32 v[8:9], v[2:3], v[8:9] op_sel:[1,0]
	v_pk_mul_f32 v[2:3], v[2:3], v[4:5] op_sel:[1,0]
	v_pk_fma_f32 v[8:9], v[34:35], v[8:9], v[38:39]
	v_pk_fma_f32 v[2:3], v[36:37], v[2:3], v[40:41]
	s_nop 0
	v_cndmask_b32_e32 v5, v211, v3, vcc
	v_cndmask_b32_e32 v4, v211, v2, vcc
	v_cndmask_b32_e32 v3, v211, v9, vcc
	v_cndmask_b32_e32 v2, v211, v8, vcc
	flat_store_dwordx4 v[112:113], v[2:5] offset:576
	s_nop 1
	v_cvt_pk_bf16_f32 v2, v2, v3
	v_cvt_pk_bf16_f32 v3, v4, v5
	flat_store_dwordx2 v[6:7], v[2:3]
	ds_read_b64 v[2:3], v0 offset:9472
	v_lshl_add_u64 v[4:5], v[118:119], 0, v[138:139]
	v_lshl_add_u64 v[6:7], v[4:5], 1, s[0:1]
	s_waitcnt lgkmcnt(0)
	v_sub_f32_e32 v5, v29, v2
	v_sub_f32_e32 v4, v28, v2
	v_sub_f32_e32 v9, v27, v2
	v_sub_f32_e32 v8, v26, v2
	v_pk_mul_f32 v[8:9], v[2:3], v[8:9] op_sel:[1,0]
	v_pk_mul_f32 v[2:3], v[2:3], v[4:5] op_sel:[1,0]
	v_pk_fma_f32 v[8:9], v[34:35], v[8:9], v[38:39]
	v_pk_fma_f32 v[2:3], v[36:37], v[2:3], v[40:41]
	s_nop 0
	v_cndmask_b32_e32 v5, v211, v3, vcc
	v_cndmask_b32_e32 v4, v211, v2, vcc
	v_cndmask_b32_e32 v3, v211, v9, vcc
	v_cndmask_b32_e32 v2, v211, v8, vcc
	flat_store_dwordx4 v[110:111], v[2:5] offset:576
	s_nop 1
	v_cvt_pk_bf16_f32 v2, v2, v3
	v_cvt_pk_bf16_f32 v3, v4, v5
	flat_store_dwordx2 v[6:7], v[2:3]
	ds_read_b64 v[2:3], v0 offset:9600
	v_lshl_add_u64 v[6:7], v[116:117], 0, v[138:139]
	s_waitcnt lgkmcnt(0)
	v_sub_f32_e32 v5, v33, v2
	v_sub_f32_e32 v4, v32, v2
	v_sub_f32_e32 v9, v31, v2
	v_sub_f32_e32 v8, v30, v2
	v_pk_mul_f32 v[8:9], v[2:3], v[8:9] op_sel:[1,0]
	v_pk_mul_f32 v[2:3], v[2:3], v[4:5] op_sel:[1,0]
	v_pk_fma_f32 v[8:9], v[34:35], v[8:9], v[38:39]
	v_pk_fma_f32 v[2:3], v[36:37], v[2:3], v[40:41]
	s_nop 0
	v_cndmask_b32_e32 v5, v211, v3, vcc
	v_cndmask_b32_e32 v4, v211, v2, vcc
	v_cndmask_b32_e32 v3, v211, v9, vcc
	v_cndmask_b32_e32 v2, v211, v8, vcc
	flat_store_dwordx4 v[114:115], v[2:5] offset:576
	s_nop 1
	v_cvt_pk_bf16_f32 v2, v2, v3
	v_cvt_pk_bf16_f32 v3, v4, v5
	v_lshl_add_u64 v[4:5], v[6:7], 1, s[0:1]
	flat_store_dwordx2 v[4:5], v[2:3]

.LBB0_1409:
	s_add_i32 s0, s33, 0x200e0
	v_mov_b32_e32 v0, s0
	s_barrier
	ds_read_b64 v[74:75], v0
	s_lshl_b32 s0, s47, 5
	s_lshl_b32 s20, s46, 8
	v_add_u32_e32 v160, s20, v174
	v_ashrrev_i32_e32 v161, 31, v160
	s_waitcnt lgkmcnt(0)
	v_readfirstlane_b32 s1, v75
	v_readfirstlane_b32 s2, v74
	v_or_b32_e32 v150, 16, v160
	v_mov_b32_e32 v75, s1
	s_add_i32 s1, s33, 0x200e8
	v_mov_b32_e32 v0, s1
	s_lshl_b32 s1, s6, 8
	ds_read_b64 v[170:171], v0
	s_or_b32 s0, s1, s0
	v_lshrrev_b32_e32 v0, 2, v172
	v_and_or_b32 v146, v0, 12, s0
	v_mov_b32_e32 v74, s2
	v_ashrrev_i32_e32 v147, 31, v146
	v_lshl_add_u64 v[158:159], v[146:147], 2, v[74:75]
	v_lshlrev_b64 v[74:75], 12, v[160:161]
	v_lshl_add_u64 v[148:149], v[158:159], 0, v[74:75]
	v_mov_b64_e32 v[246:247], v[148:149]
	global_load_dwordx4 v[218:221], v[246:247], off
	global_load_dwordx4 v[222:225], v[246:247], off offset:64
	global_load_dwordx4 v[196:199], v[246:247], off offset:512
	global_load_dwordx4 v[248:251], v[246:247], off offset:576
	s_mov_b32 s100, 0x10000
	s_mov_b32 s101, 0
	v_lshl_add_u64 v[230:231], v[246:247], 0, s[100:101]
	global_load_dwordx4 v[234:237], v[230:231], off offset:64
	global_load_dwordx4 v[238:241], v[230:231], off offset:512
	global_load_dwordx4 v[242:245], v[230:231], off offset:576
	global_load_dwordx4 v[230:233], v[230:231], off
	v_ashrrev_i32_e32 v151, 31, v150
	v_lshlrev_b64 v[150:151], 12, v[150:151]
	s_mov_b32 s0, 0x3fb504f3
	v_lshl_add_u64 v[150:151], v[158:159], 0, v[150:151]
	v_add_u32_e32 v162, 0x80, v160
	v_ashrrev_i32_e32 v163, 31, v162
	v_add_u32_e32 v164, 0x90, v160
	v_ashrrev_i32_e32 v165, 31, v164
	v_lshlrev_b64 v[152:153], 12, v[164:165]
	v_lshl_add_u64 v[152:153], v[158:159], 0, v[152:153]
	v_add_u32_e32 v166, 0xa0, v160
	v_ashrrev_i32_e32 v167, 31, v166
	v_lshlrev_b64 v[154:155], 12, v[166:167]
	v_lshl_add_u64 v[154:155], v[158:159], 0, v[154:155]
	v_add_u32_e32 v168, 0xb0, v160
	v_and_b32_e32 v156, 64, v204
	v_ashrrev_i32_e32 v169, 31, v168
	v_add_u32_e32 v175, 64, v156
	v_lshlrev_b64 v[156:157], 12, v[168:169]
	v_lshl_add_u64 v[156:157], v[158:159], 0, v[156:157]
	v_xor_b32_e32 v0, 16, v204
	v_cmp_lt_i32_e32 vcc, v0, v175
	s_waitcnt lgkmcnt(0)
	v_readfirstlane_b32 s22, v170
	v_readfirstlane_b32 s21, v171
	v_cndmask_b32_e32 v0, v204, v0, vcc
	v_lshlrev_b32_e32 v0, 2, v0
	s_waitcnt vmcnt(4) lgkmcnt(0)
	v_pk_fma_f32 v[76:77], v[220:221], s[0:1], v[4:5] op_sel_hi:[1,0,1]
	v_pk_fma_f32 v[74:75], v[218:219], s[0:1], v[2:3] op_sel_hi:[1,0,1]
	v_pk_fma_f32 v[44:45], v[224:225], s[0:1], v[44:45] op_sel_hi:[1,0,1]
	v_pk_fma_f32 v[42:43], v[222:223], s[0:1], v[42:43] op_sel_hi:[1,0,1]
	v_pk_fma_f32 v[20:21], v[198:199], s[0:1], v[20:21] op_sel_hi:[1,0,1]
	v_pk_fma_f32 v[18:19], v[196:197], s[0:1], v[18:19] op_sel_hi:[1,0,1]
	v_pk_fma_f32 v[4:5], v[250:251], s[0:1], v[132:133] op_sel_hi:[1,0,1]
	v_pk_fma_f32 v[2:3], v[248:249], s[0:1], v[130:131] op_sel_hi:[1,0,1]
	s_nop 0
	s_mov_b32 s100, 0x20000
	s_mov_b32 s101, 0
	v_lshl_add_u64 v[134:135], v[246:247], 0, s[100:101]
	global_load_dwordx4 v[138:141], v[134:135], off offset:64
	global_load_dwordx4 v[142:145], v[134:135], off offset:512
	global_load_dwordx4 v[130:133], v[134:135], off offset:576
	global_load_dwordx4 v[134:137], v[134:135], off
	s_mov_b32 s100, 0x30000
	s_mov_b32 s101, 0
	v_lshl_add_u64 v[218:219], v[246:247], 0, s[100:101]
	global_load_dwordx4 v[222:225], v[218:219], off offset:64
	global_load_dwordx4 v[196:199], v[218:219], off offset:512
	global_load_dwordx4 v[248:251], v[218:219], off offset:576
	global_load_dwordx4 v[218:221], v[218:219], off
	v_or_b32_e32 v150, 32, v160
	v_ashrrev_i32_e32 v151, 31, v150
	v_lshlrev_b64 v[150:151], 12, v[150:151]
	v_lshl_add_u64 v[150:151], v[158:159], 0, v[150:151]
	v_mov_b32_e32 v176, v75
	v_mov_b32_e32 v177, v76
	v_mov_b32_e32 v182, v74
	v_mov_b32_e32 v183, v77
	v_mov_b32_e32 v184, v43
	v_mov_b32_e32 v185, v44
	v_mov_b32_e32 v186, v42
	v_mov_b32_e32 v187, v45
	v_pk_add_f32 v[176:177], v[176:177], v[182:183]
	v_pk_add_f32 v[182:183], v[184:185], v[186:187]
	v_add_f32_e32 v178, v176, v177
	v_pk_add_f32 v[176:177], v[182:183], v[182:183] op_sel_hi:[0,1]
	v_add_f32_e32 v189, v18, v19
	v_add_f32_e32 v191, v20, v21
	v_mov_b32_e32 v188, v2
	v_mov_b32_e32 v190, v3
	v_mov_b32_e32 v192, v5
	v_add_f32_e32 v193, 0, v178
	v_mov_b32_e32 v176, v4
	v_pk_add_f32 v[184:185], v[188:189], v[190:191]
	v_pk_add_f32 v[176:177], v[176:177], v[192:193]
	v_xor_b32_e32 v178, 32, v204
	v_pk_add_f32 v[176:177], v[184:185], v[176:177]
	v_cmp_lt_i32_e32 vcc, v178, v175
	v_add_f32_e32 v176, v176, v177
	ds_bpermute_b32 v177, v0, v176
	v_cndmask_b32_e32 v175, v204, v178, vcc
	v_lshlrev_b32_e32 v175, 2, v175
	s_waitcnt lgkmcnt(0)
	v_add_f32_e32 v176, v176, v177
	ds_bpermute_b32 v177, v175, v176
	s_waitcnt lgkmcnt(0)
	v_add_f32_e32 v177, v176, v177
	v_fmamk_f32 v178, v177, 0xbc800000, v77
	v_fmamk_f32 v183, v177, 0xbc800000, v75
	v_fmamk_f32 v185, v177, 0xbc800000, v45
	v_fmamk_f32 v187, v177, 0xbc800000, v43
	v_fmamk_f32 v176, v177, 0xbc800000, v76
	v_fmamk_f32 v182, v177, 0xbc800000, v74
	v_fmamk_f32 v184, v177, 0xbc800000, v44
	v_fmamk_f32 v186, v177, 0xbc800000, v42
	v_fmamk_f32 v189, v177, 0xbc800000, v21
	v_fmamk_f32 v191, v177, 0xbc800000, v19
	v_mul_f32_e32 v183, v183, v183
	v_mul_f32_e32 v178, v178, v178
	v_mul_f32_e32 v187, v187, v187
	v_mul_f32_e32 v185, v185, v185
	v_fmamk_f32 v188, v177, 0xbc800000, v20
	v_fmamk_f32 v190, v177, 0xbc800000, v18
	v_fmamk_f32 v193, v177, 0xbc800000, v5
	v_fmamk_f32 v195, v177, 0xbc800000, v3
	v_mul_f32_e32 v191, v191, v191
	v_mul_f32_e32 v189, v189, v189
	v_fmac_f32_e32 v183, v182, v182
	v_fmac_f32_e32 v178, v176, v176
	v_fmac_f32_e32 v187, v186, v186
	v_fmac_f32_e32 v185, v184, v184
	v_fmamk_f32 v192, v177, 0xbc800000, v4
	v_fmamk_f32 v194, v177, 0xbc800000, v2
	v_mul_f32_e32 v195, v195, v195
	v_mul_f32_e32 v193, v193, v193
	v_fmac_f32_e32 v191, v190, v190
	v_fmac_f32_e32 v189, v188, v188
	v_add_f32_e32 v176, v183, v178
	v_add_f32_e32 v178, v187, v185
	v_fmac_f32_e32 v195, v194, v194
	v_fmac_f32_e32 v193, v192, v192
	v_add_f32_e32 v182, v191, v189
	s_waitcnt vmcnt(8) lgkmcnt(0)
	v_pk_fma_f32 v[88:89], v[232:233], s[0:1], v[88:89] op_sel_hi:[1,0,1]
	v_pk_fma_f32 v[86:87], v[230:231], s[0:1], v[86:87] op_sel_hi:[1,0,1]
	v_pk_fma_f32 v[56:57], v[236:237], s[0:1], v[56:57] op_sel_hi:[1,0,1]
	v_pk_fma_f32 v[54:55], v[234:235], s[0:1], v[54:55] op_sel_hi:[1,0,1]
	v_pk_fma_f32 v[28:29], v[240:241], s[0:1], v[28:29] op_sel_hi:[1,0,1]
	v_pk_fma_f32 v[26:27], v[238:239], s[0:1], v[26:27] op_sel_hi:[1,0,1]
	v_pk_fma_f32 v[8:9], v[244:245], s[0:1], v[8:9] op_sel_hi:[1,0,1]
	v_pk_fma_f32 v[6:7], v[242:243], s[0:1], v[6:7] op_sel_hi:[1,0,1]
	v_add_f32_e32 v176, v176, v178
	s_mov_b32 s100, 0x80000
	s_mov_b32 s101, 0
	v_lshl_add_u64 v[230:231], v[246:247], 0, s[100:101]
	global_load_dwordx4 v[234:237], v[230:231], off offset:64
	global_load_dwordx4 v[238:241], v[230:231], off offset:512
	global_load_dwordx4 v[242:245], v[230:231], off offset:576
	global_load_dwordx4 v[230:233], v[230:231], off
	v_or_b32_e32 v150, 48, v160
	v_ashrrev_i32_e32 v151, 31, v150
	v_lshlrev_b64 v[150:151], 12, v[150:151]
	v_lshl_add_u64 v[150:151], v[158:159], 0, v[150:151]
	v_add_f32_e32 v183, v195, v193
	v_add_f32_e32 v176, v182, v176
	v_add_f32_e32 v178, v183, v176
	ds_bpermute_b32 v182, v0, v178
	v_and_b32_e32 v176, 63, v172
	v_cmp_gt_u32_e32 vcc, 16, v176
	s_waitcnt lgkmcnt(0)
	v_add_f32_e32 v170, v178, v182
	ds_bpermute_b32 v171, v175, v170
	s_waitcnt vmcnt(8) lgkmcnt(0)
	v_pk_fma_f32 v[96:97], v[136:137], s[0:1], v[96:97] op_sel_hi:[1,0,1]
	v_pk_fma_f32 v[94:95], v[134:135], s[0:1], v[94:95] op_sel_hi:[1,0,1]
	v_pk_fma_f32 v[64:65], v[140:141], s[0:1], v[64:65] op_sel_hi:[1,0,1]
	v_pk_fma_f32 v[62:63], v[138:139], s[0:1], v[62:63] op_sel_hi:[1,0,1]
	v_pk_fma_f32 v[36:37], v[144:145], s[0:1], v[36:37] op_sel_hi:[1,0,1]
	v_pk_fma_f32 v[34:35], v[142:143], s[0:1], v[34:35] op_sel_hi:[1,0,1]
	v_pk_fma_f32 v[12:13], v[132:133], s[0:1], v[12:13] op_sel_hi:[1,0,1]
	v_pk_fma_f32 v[10:11], v[130:131], s[0:1], v[10:11] op_sel_hi:[1,0,1]
	s_nop 0
	s_mov_b32 s100, 0x90000
	s_mov_b32 s101, 0
	v_lshl_add_u64 v[134:135], v[246:247], 0, s[100:101]
	global_load_dwordx4 v[138:141], v[134:135], off offset:64
	global_load_dwordx4 v[142:145], v[134:135], off offset:512
	global_load_dwordx4 v[130:133], v[134:135], off offset:576
	global_load_dwordx4 v[134:137], v[134:135], off
	v_lshlrev_b64 v[150:151], 12, v[162:163]
	v_lshl_add_u64 v[150:151], v[158:159], 0, v[150:151]
	s_waitcnt vmcnt(8) lgkmcnt(0)
	v_pk_fma_f32 v[100:101], v[220:221], s[0:1], v[100:101] op_sel_hi:[1,0,1]
	v_pk_fma_f32 v[98:99], v[218:219], s[0:1], v[98:99] op_sel_hi:[1,0,1]
	v_pk_fma_f32 v[68:69], v[224:225], s[0:1], v[68:69] op_sel_hi:[1,0,1]
	v_pk_fma_f32 v[66:67], v[222:223], s[0:1], v[66:67] op_sel_hi:[1,0,1]
	v_pk_fma_f32 v[40:41], v[198:199], s[0:1], v[40:41] op_sel_hi:[1,0,1]
	v_pk_fma_f32 v[38:39], v[196:197], s[0:1], v[38:39] op_sel_hi:[1,0,1]
	v_pk_fma_f32 v[16:17], v[250:251], s[0:1], v[16:17] op_sel_hi:[1,0,1]
	v_pk_fma_f32 v[14:15], v[248:249], s[0:1], v[14:15] op_sel_hi:[1,0,1]
	s_nop 0
	s_mov_b32 s100, 0xa0000
	s_mov_b32 s101, 0
	v_lshl_add_u64 v[218:219], v[246:247], 0, s[100:101]
	global_load_dwordx4 v[222:225], v[218:219], off offset:64
	global_load_dwordx4 v[196:199], v[218:219], off offset:512
	global_load_dwordx4 v[248:251], v[218:219], off offset:576
	global_load_dwordx4 v[218:221], v[218:219], off
	s_waitcnt vmcnt(8) lgkmcnt(0)
	v_pk_fma_f32 v[104:105], v[232:233], s[0:1], v[104:105] op_sel_hi:[1,0,1]
	v_pk_fma_f32 v[102:103], v[230:231], s[0:1], v[102:103] op_sel_hi:[1,0,1]
	v_pk_fma_f32 v[72:73], v[236:237], s[0:1], v[72:73] op_sel_hi:[1,0,1]
	v_pk_fma_f32 v[70:71], v[234:235], s[0:1], v[70:71] op_sel_hi:[1,0,1]
	v_pk_fma_f32 v[48:49], v[240:241], s[0:1], v[48:49] op_sel_hi:[1,0,1]
	v_pk_fma_f32 v[46:47], v[238:239], s[0:1], v[46:47] op_sel_hi:[1,0,1]
	v_pk_fma_f32 v[24:25], v[244:245], s[0:1], v[24:25] op_sel_hi:[1,0,1]
	v_pk_fma_f32 v[22:23], v[242:243], s[0:1], v[22:23] op_sel_hi:[1,0,1]
	s_nop 0
	s_mov_b32 s100, 0xb0000
	s_mov_b32 s101, 0
	v_lshl_add_u64 v[230:231], v[246:247], 0, s[100:101]
	global_load_dwordx4 v[234:237], v[230:231], off offset:64
	global_load_dwordx4 v[238:241], v[230:231], off offset:512
	global_load_dwordx4 v[242:245], v[230:231], off offset:576
	global_load_dwordx4 v[230:233], v[230:231], off
	s_waitcnt vmcnt(8) lgkmcnt(0)
	v_pk_fma_f32 v[116:117], v[136:137], s[0:1], v[116:117] op_sel_hi:[1,0,1]
	v_pk_fma_f32 v[114:115], v[134:135], s[0:1], v[114:115] op_sel_hi:[1,0,1]
	v_pk_fma_f32 v[92:93], v[140:141], s[0:1], v[92:93] op_sel_hi:[1,0,1]
	v_pk_fma_f32 v[90:91], v[138:139], s[0:1], v[90:91] op_sel_hi:[1,0,1]
	v_pk_fma_f32 v[60:61], v[144:145], s[0:1], v[60:61] op_sel_hi:[1,0,1]
	v_pk_fma_f32 v[58:59], v[142:143], s[0:1], v[58:59] op_sel_hi:[1,0,1]
	v_pk_fma_f32 v[32:33], v[132:133], s[0:1], v[32:33] op_sel_hi:[1,0,1]
	v_pk_fma_f32 v[30:31], v[130:131], s[0:1], v[30:31] op_sel_hi:[1,0,1]
	s_nop 0
	s_waitcnt vmcnt(4) lgkmcnt(0)
	v_pk_fma_f32 v[128:129], v[220:221], s[0:1], v[128:129] op_sel_hi:[1,0,1]
	v_pk_fma_f32 v[126:127], v[218:219], s[0:1], v[126:127] op_sel_hi:[1,0,1]
	v_pk_fma_f32 v[112:113], v[224:225], s[0:1], v[112:113] op_sel_hi:[1,0,1]
	v_pk_fma_f32 v[110:111], v[222:223], s[0:1], v[110:111] op_sel_hi:[1,0,1]
	v_pk_fma_f32 v[84:85], v[198:199], s[0:1], v[84:85] op_sel_hi:[1,0,1]
	v_pk_fma_f32 v[82:83], v[196:197], s[0:1], v[82:83] op_sel_hi:[1,0,1]
	v_pk_fma_f32 v[52:53], v[250:251], s[0:1], v[52:53] op_sel_hi:[1,0,1]
	v_pk_fma_f32 v[50:51], v[248:249], s[0:1], v[50:51] op_sel_hi:[1,0,1]
	s_nop 0
	s_waitcnt vmcnt(0) lgkmcnt(0)
	v_pk_fma_f32 v[124:125], v[232:233], s[0:1], v[124:125] op_sel_hi:[1,0,1]
	v_pk_fma_f32 v[122:123], v[230:231], s[0:1], v[122:123] op_sel_hi:[1,0,1]
	v_pk_fma_f32 v[120:121], v[236:237], s[0:1], v[120:121] op_sel_hi:[1,0,1]
	v_pk_fma_f32 v[118:119], v[234:235], s[0:1], v[118:119] op_sel_hi:[1,0,1]
	v_pk_fma_f32 v[108:109], v[240:241], s[0:1], v[108:109] op_sel_hi:[1,0,1]
	v_pk_fma_f32 v[106:107], v[238:239], s[0:1], v[106:107] op_sel_hi:[1,0,1]
	v_pk_fma_f32 v[80:81], v[244:245], s[0:1], v[80:81] op_sel_hi:[1,0,1]
	v_pk_fma_f32 v[78:79], v[242:243], s[0:1], v[78:79] op_sel_hi:[1,0,1]
	s_lshl_b32 s0, s47, 3
	s_add_i32 s2, s16, s0
	s_and_saveexec_b64 s[0:1], vcc
	s_mul_i32 s60, s36, 0x600
	v_readlane_b32 s61, v252, 14
	v_readlane_b32 s62, v252, 15
	v_readlane_b32 s53, v252, 16
	v_readlane_b32 s54, v252, 17
	s_movk_i32 s55, 0x6000
	s_mov_b32 s58, 0x3fb8aa3b
	s_movk_i32 s59, 0xe80
	s_mov_b32 s63, 0xc2fc0000
	s_mov_b32 s66, 0x1ffff
	s_movk_i32 s67, 0x1ff
	s_cbranch_execz .LBB0_1411
	s_lshl_b32 s3, s44, 11
	s_add_i32 s3, s2, s3
	v_mul_f32_e32 v130, 0x3c800000, v177
	v_add_f32_e32 v131, v170, v171
	v_lshl_add_u32 v132, v173, 5, s3
	ds_write_b64 v132, v[130:131]

.LBB0_1448:
	s_or_b64 exec, exec, s[0:1]
	s_add_i32 s0, s33, 0x200d0
	s_waitcnt lgkmcnt(0)
	s_barrier
	v_mov_b32_e32 v0, s0
	ds_read_b64 v[130:131], v0
	v_readlane_b32 s0, v252, 6
	s_lshl_b32 s44, s0, 10
	s_lshl_b64 s[0:1], s[44:45], 2
	v_lshlrev_b64 v[132:133], 2, v[146:147]
	s_waitcnt lgkmcnt(0)
	v_readfirstlane_b32 s2, v130
	v_readfirstlane_b32 s3, v131
	s_add_u32 s2, s2, s0
	s_addc_u32 s3, s3, s1
	s_add_i32 s4, s33, 0x200d8
	v_mov_b32_e32 v0, s4
	ds_read_b64 v[130:131], v0
	v_lshl_add_u64 v[140:141], s[2:3], 0, v[132:133]
	v_lshl_add_u32 v0, v174, 3, s16
	v_readlane_b32 s6, v252, 21
	v_readlane_b32 s7, v252, 22
	s_waitcnt lgkmcnt(0)
	v_readfirstlane_b32 s3, v130
	v_readfirstlane_b32 s2, v131
	s_add_u32 s0, s3, s0
	s_addc_u32 s1, s2, s1
	v_lshl_add_u64 v[142:143], s[0:1], 0, v[132:133]
	flat_load_dwordx4 v[130:133], v[140:141]
	flat_load_dwordx4 v[134:137], v[142:143]
	global_load_dwordx4 v[182:185], v[140:141], off offset:64
	global_load_dwordx4 v[186:189], v[142:143], off offset:64
	global_load_dwordx4 v[190:193], v[140:141], off offset:512
	global_load_dwordx4 v[194:197], v[142:143], off offset:512
	global_load_dwordx4 v[218:221], v[140:141], off offset:576
	global_load_dwordx4 v[222:225], v[142:143], off offset:576
	ds_read_b64 v[170:171], v0 offset:8192
	v_cndmask_b32_e64 v145, 0, 1, s[6:7]
	s_add_u32 s0, s22, 0x4bf0000
	v_cmp_eq_u32_e64 s[4:5], 0, v144
	v_lshlrev_b64 v[138:139], 10, v[160:161]
	s_waitcnt lgkmcnt(0)
	v_sub_f32_e32 v77, v77, v170
	v_sub_f32_e32 v76, v76, v170
	v_sub_f32_e32 v75, v75, v170
	v_sub_f32_e32 v74, v74, v170
	v_pk_mul_f32 v[74:75], v[170:171], v[74:75] op_sel:[1,0]
	v_pk_mul_f32 v[76:77], v[170:171], v[76:77] op_sel:[1,0]
	v_cmp_ne_u32_e64 s[2:3], 1, v145
	s_addc_u32 s1, s21, 0
	s_andn2_b64 vcc, exec, s[6:7]
	s_waitcnt vmcnt(0)
	v_pk_fma_f32 v[76:77], v[132:133], v[76:77], v[136:137]
	v_pk_fma_f32 v[74:75], v[130:131], v[74:75], v[134:135]
	v_cndmask_b32_e64 v77, v211, v77, s[4:5]
	v_cndmask_b32_e64 v76, v211, v76, s[4:5]
	v_cndmask_b32_e64 v75, v211, v75, s[4:5]
	v_cndmask_b32_e64 v74, v211, v74, s[4:5]
	flat_store_dwordx4 v[148:149], v[74:77]
	s_cbranch_vccnz .LBB0_1450
	v_lshl_add_u64 v[144:145], v[138:139], 0, v[146:147]
	v_cvt_pk_bf16_f32 v74, v74, v75
	v_cvt_pk_bf16_f32 v75, v76, v77
	v_lshl_add_u64 v[76:77], v[144:145], 1, s[0:1]
	flat_store_dwordx2 v[76:77], v[74:75]

.LBB0_1464:
	s_nop 1
	v_mov_b32_e32 v74, v182
	v_mov_b32_e32 v75, v183
	v_mov_b32_e32 v76, v184
	v_mov_b32_e32 v77, v185
	s_nop 0
	s_nop 1
	v_mov_b32_e32 v86, v186
	v_mov_b32_e32 v87, v187
	v_mov_b32_e32 v88, v188
	v_mov_b32_e32 v89, v189
	ds_read_b64 v[114:115], v0 offset:8192
	v_or_b32_e32 v104, 16, v146
	v_mov_b32_e32 v105, v147
	s_and_b64 vcc, exec, s[2:3]
	s_waitcnt lgkmcnt(0)
	v_sub_f32_e32 v43, v43, v114
	v_sub_f32_e32 v42, v42, v114
	v_sub_f32_e32 v45, v45, v114
	v_sub_f32_e32 v44, v44, v114
	v_pk_mul_f32 v[44:45], v[114:115], v[44:45] op_sel:[1,0]
	v_pk_mul_f32 v[42:43], v[114:115], v[42:43] op_sel:[1,0]
	s_nop 0
	v_pk_fma_f32 v[44:45], v[76:77], v[44:45], v[88:89]
	v_pk_fma_f32 v[42:43], v[74:75], v[42:43], v[86:87]
	v_cndmask_b32_e64 v45, v211, v45, s[4:5]
	v_cndmask_b32_e64 v44, v211, v44, s[4:5]
	v_cndmask_b32_e64 v43, v211, v43, s[4:5]
	v_cndmask_b32_e64 v42, v211, v42, s[4:5]
	flat_store_dwordx4 v[148:149], v[42:45] offset:64
	s_cbranch_vccnz .LBB0_1466
	v_lshl_add_u64 v[114:115], v[138:139], 0, v[104:105]
	v_cvt_pk_bf16_f32 v42, v42, v43
	v_cvt_pk_bf16_f32 v43, v44, v45
	v_lshl_add_u64 v[44:45], v[114:115], 1, s[0:1]
	flat_store_dwordx2 v[44:45], v[42:43]

.LBB0_1480:
	s_nop 1
	v_mov_b32_e32 v42, v190
	v_mov_b32_e32 v43, v191
	v_mov_b32_e32 v44, v192
	v_mov_b32_e32 v45, v193
	s_nop 0
	s_nop 1
	v_mov_b32_e32 v54, v194
	v_mov_b32_e32 v55, v195
	v_mov_b32_e32 v56, v196
	v_mov_b32_e32 v57, v197
	ds_read_b64 v[64:65], v0 offset:8192
	v_or_b32_e32 v62, 0x80, v146
	v_mov_b32_e32 v63, v147
	s_and_b64 vcc, exec, s[2:3]
	s_waitcnt lgkmcnt(0)
	v_sub_f32_e32 v19, v19, v64
	v_sub_f32_e32 v18, v18, v64
	v_sub_f32_e32 v21, v21, v64
	v_sub_f32_e32 v20, v20, v64
	v_pk_mul_f32 v[20:21], v[64:65], v[20:21] op_sel:[1,0]
	v_pk_mul_f32 v[18:19], v[64:65], v[18:19] op_sel:[1,0]
	s_nop 0
	v_pk_fma_f32 v[20:21], v[44:45], v[20:21], v[56:57]
	v_pk_fma_f32 v[18:19], v[42:43], v[18:19], v[54:55]
	v_cndmask_b32_e64 v21, v211, v21, s[4:5]
	v_cndmask_b32_e64 v20, v211, v20, s[4:5]
	v_cndmask_b32_e64 v19, v211, v19, s[4:5]
	v_cndmask_b32_e64 v18, v211, v18, s[4:5]
	flat_store_dwordx4 v[148:149], v[18:21] offset:512
	s_cbranch_vccnz .LBB0_1482
	v_lshl_add_u64 v[64:65], v[138:139], 0, v[62:63]
	v_cvt_pk_bf16_f32 v18, v18, v19
	v_cvt_pk_bf16_f32 v19, v20, v21
	v_lshl_add_u64 v[20:21], v[64:65], 1, s[0:1]
	flat_store_dwordx2 v[20:21], v[18:19]

.LBB0_1496:
	s_nop 1
	v_mov_b32_e32 v18, v218
	v_mov_b32_e32 v19, v219
	v_mov_b32_e32 v20, v220
	v_mov_b32_e32 v21, v221
	s_nop 0
	s_nop 1
	v_mov_b32_e32 v26, v222
	v_mov_b32_e32 v27, v223
	v_mov_b32_e32 v28, v224
	v_mov_b32_e32 v29, v225
	ds_read_b64 v[34:35], v0 offset:8192
	v_or_b32_e32 v146, 0x90, v146
	s_and_b64 vcc, exec, s[2:3]
	s_waitcnt lgkmcnt(0)
	v_sub_f32_e32 v3, v3, v34
	v_sub_f32_e32 v2, v2, v34
	v_sub_f32_e32 v5, v5, v34
	v_sub_f32_e32 v4, v4, v34
	v_pk_mul_f32 v[4:5], v[34:35], v[4:5] op_sel:[1,0]
	v_pk_mul_f32 v[2:3], v[34:35], v[2:3] op_sel:[1,0]
	s_nop 0
	v_pk_fma_f32 v[4:5], v[20:21], v[4:5], v[28:29]
	v_pk_fma_f32 v[2:3], v[18:19], v[2:3], v[26:27]
	v_cndmask_b32_e64 v5, v211, v5, s[4:5]
	v_cndmask_b32_e64 v4, v211, v4, s[4:5]
	v_cndmask_b32_e64 v3, v211, v3, s[4:5]
	v_cndmask_b32_e64 v2, v211, v2, s[4:5]
	flat_store_dwordx4 v[148:149], v[2:5] offset:576
	s_cbranch_vccnz .LBB0_1498
	v_lshl_add_u64 v[34:35], v[138:139], 0, v[146:147]
	v_cvt_pk_bf16_f32 v2, v2, v3
	v_cvt_pk_bf16_f32 v3, v4, v5
	v_lshl_add_u64 v[4:5], v[34:35], 1, s[0:1]
	flat_store_dwordx2 v[4:5], v[2:3]

.LBB0_1531:
	s_add_i32 s0, s33, 0x200e0
	v_mov_b32_e32 v0, s0
	s_barrier
	ds_read_b64 v[74:75], v0
	s_lshl_b32 s0, s46, 5
	s_add_i32 s21, s62, 64
	s_lshl_b32 s20, s21, 8
	v_add_u32_e32 v160, s20, v174
	s_waitcnt lgkmcnt(0)
	v_readfirstlane_b32 s1, v75
	v_readfirstlane_b32 s2, v74
	v_ashrrev_i32_e32 v161, 31, v160
	v_mov_b32_e32 v75, s1
	s_add_i32 s1, s33, 0x200e8
	v_mov_b32_e32 v0, s1
	s_lshl_b32 s1, s6, 8
	ds_read_b64 v[170:171], v0
	s_or_b32 s0, s1, s0
	v_lshrrev_b32_e32 v0, 2, v172
	v_and_or_b32 v146, v0, 12, s0
	v_mov_b32_e32 v74, s2
	v_ashrrev_i32_e32 v147, 31, v146
	v_lshl_add_u64 v[158:159], v[146:147], 2, v[74:75]
	v_lshlrev_b64 v[74:75], 12, v[160:161]
	v_lshl_add_u64 v[148:149], v[158:159], 0, v[74:75]
	v_mov_b64_e32 v[246:247], v[148:149]
	global_load_dwordx4 v[218:221], v[246:247], off
	global_load_dwordx4 v[222:225], v[246:247], off offset:64
	global_load_dwordx4 v[196:199], v[246:247], off offset:512
	global_load_dwordx4 v[248:251], v[246:247], off offset:576
	s_mov_b32 s100, 0x10000
	s_mov_b32 s101, 0
	v_lshl_add_u64 v[230:231], v[246:247], 0, s[100:101]
	global_load_dwordx4 v[234:237], v[230:231], off offset:64
	global_load_dwordx4 v[238:241], v[230:231], off offset:512
	global_load_dwordx4 v[242:245], v[230:231], off offset:576
	global_load_dwordx4 v[230:233], v[230:231], off
	v_or_b32_e32 v150, 16, v160
	v_ashrrev_i32_e32 v151, 31, v150
	v_lshlrev_b64 v[150:151], 12, v[150:151]
	s_mov_b32 s0, 0x3fb504f3
	v_lshl_add_u64 v[150:151], v[158:159], 0, v[150:151]
	v_add_u32_e32 v162, 0x80, v160
	v_ashrrev_i32_e32 v163, 31, v162
	v_add_u32_e32 v164, 0x90, v160
	v_ashrrev_i32_e32 v165, 31, v164
	v_lshlrev_b64 v[152:153], 12, v[164:165]
	v_lshl_add_u64 v[152:153], v[158:159], 0, v[152:153]
	v_add_u32_e32 v166, 0xa0, v160
	v_ashrrev_i32_e32 v167, 31, v166
	v_lshlrev_b64 v[154:155], 12, v[166:167]
	v_lshl_add_u64 v[154:155], v[158:159], 0, v[154:155]
	v_add_u32_e32 v168, 0xb0, v160
	v_and_b32_e32 v156, 64, v204
	v_ashrrev_i32_e32 v169, 31, v168
	v_add_u32_e32 v175, 64, v156
	v_lshlrev_b64 v[156:157], 12, v[168:169]
	v_lshl_add_u64 v[156:157], v[158:159], 0, v[156:157]
	v_xor_b32_e32 v0, 16, v204
	v_cmp_lt_i32_e32 vcc, v0, v175
	s_waitcnt lgkmcnt(0)
	v_readfirstlane_b32 s23, v170
	v_readfirstlane_b32 s22, v171
	v_cndmask_b32_e32 v0, v204, v0, vcc
	v_lshlrev_b32_e32 v0, 2, v0
	s_waitcnt vmcnt(4) lgkmcnt(0)
	v_pk_fma_f32 v[76:77], v[220:221], s[0:1], v[4:5] op_sel_hi:[1,0,1]
	v_pk_fma_f32 v[74:75], v[218:219], s[0:1], v[2:3] op_sel_hi:[1,0,1]
	v_pk_fma_f32 v[44:45], v[224:225], s[0:1], v[44:45] op_sel_hi:[1,0,1]
	v_pk_fma_f32 v[42:43], v[222:223], s[0:1], v[42:43] op_sel_hi:[1,0,1]
	v_pk_fma_f32 v[20:21], v[198:199], s[0:1], v[20:21] op_sel_hi:[1,0,1]
	v_pk_fma_f32 v[18:19], v[196:197], s[0:1], v[18:19] op_sel_hi:[1,0,1]
	v_pk_fma_f32 v[4:5], v[250:251], s[0:1], v[132:133] op_sel_hi:[1,0,1]
	v_pk_fma_f32 v[2:3], v[248:249], s[0:1], v[130:131] op_sel_hi:[1,0,1]
	s_nop 0
	s_mov_b32 s100, 0x20000
	s_mov_b32 s101, 0
	v_lshl_add_u64 v[134:135], v[246:247], 0, s[100:101]
	global_load_dwordx4 v[138:141], v[134:135], off offset:64
	global_load_dwordx4 v[142:145], v[134:135], off offset:512
	global_load_dwordx4 v[130:133], v[134:135], off offset:576
	global_load_dwordx4 v[134:137], v[134:135], off
	s_mov_b32 s100, 0x30000
	s_mov_b32 s101, 0
	v_lshl_add_u64 v[218:219], v[246:247], 0, s[100:101]
	global_load_dwordx4 v[222:225], v[218:219], off offset:64
	global_load_dwordx4 v[196:199], v[218:219], off offset:512
	global_load_dwordx4 v[248:251], v[218:219], off offset:576
	global_load_dwordx4 v[218:221], v[218:219], off
	v_or_b32_e32 v150, 32, v160
	v_ashrrev_i32_e32 v151, 31, v150
	v_lshlrev_b64 v[150:151], 12, v[150:151]
	v_lshl_add_u64 v[150:151], v[158:159], 0, v[150:151]
	v_mov_b32_e32 v176, v75
	v_mov_b32_e32 v177, v76
	v_mov_b32_e32 v182, v74
	v_mov_b32_e32 v183, v77
	v_mov_b32_e32 v184, v43
	v_mov_b32_e32 v185, v44
	v_mov_b32_e32 v186, v42
	v_mov_b32_e32 v187, v45
	v_pk_add_f32 v[176:177], v[176:177], v[182:183]
	v_pk_add_f32 v[182:183], v[184:185], v[186:187]
	v_add_f32_e32 v178, v176, v177
	v_pk_add_f32 v[176:177], v[182:183], v[182:183] op_sel_hi:[0,1]
	v_add_f32_e32 v189, v18, v19
	v_add_f32_e32 v191, v20, v21
	v_mov_b32_e32 v188, v2
	v_mov_b32_e32 v190, v3
	v_mov_b32_e32 v192, v5
	v_add_f32_e32 v193, 0, v178
	v_mov_b32_e32 v176, v4
	v_pk_add_f32 v[184:185], v[188:189], v[190:191]
	v_pk_add_f32 v[176:177], v[176:177], v[192:193]
	v_xor_b32_e32 v178, 32, v204
	v_pk_add_f32 v[176:177], v[184:185], v[176:177]
	v_cmp_lt_i32_e32 vcc, v178, v175
	v_add_f32_e32 v176, v176, v177
	ds_bpermute_b32 v177, v0, v176
	v_cndmask_b32_e32 v175, v204, v178, vcc
	v_lshlrev_b32_e32 v175, 2, v175
	s_waitcnt lgkmcnt(0)
	v_add_f32_e32 v176, v176, v177
	ds_bpermute_b32 v177, v175, v176
	s_waitcnt lgkmcnt(0)
	v_add_f32_e32 v177, v176, v177
	v_fmamk_f32 v178, v177, 0xbc800000, v77
	v_fmamk_f32 v183, v177, 0xbc800000, v75
	v_fmamk_f32 v185, v177, 0xbc800000, v45
	v_fmamk_f32 v187, v177, 0xbc800000, v43
	v_fmamk_f32 v176, v177, 0xbc800000, v76
	v_fmamk_f32 v182, v177, 0xbc800000, v74
	v_fmamk_f32 v184, v177, 0xbc800000, v44
	v_fmamk_f32 v186, v177, 0xbc800000, v42
	v_fmamk_f32 v189, v177, 0xbc800000, v21
	v_fmamk_f32 v191, v177, 0xbc800000, v19
	v_mul_f32_e32 v183, v183, v183
	v_mul_f32_e32 v178, v178, v178
	v_mul_f32_e32 v187, v187, v187
	v_mul_f32_e32 v185, v185, v185
	v_fmamk_f32 v188, v177, 0xbc800000, v20
	v_fmamk_f32 v190, v177, 0xbc800000, v18
	v_fmamk_f32 v193, v177, 0xbc800000, v5
	v_fmamk_f32 v195, v177, 0xbc800000, v3
	v_mul_f32_e32 v191, v191, v191
	v_mul_f32_e32 v189, v189, v189
	v_fmac_f32_e32 v183, v182, v182
	v_fmac_f32_e32 v178, v176, v176
	v_fmac_f32_e32 v187, v186, v186
	v_fmac_f32_e32 v185, v184, v184
	v_fmamk_f32 v192, v177, 0xbc800000, v4
	v_fmamk_f32 v194, v177, 0xbc800000, v2
	v_mul_f32_e32 v195, v195, v195
	v_mul_f32_e32 v193, v193, v193
	v_fmac_f32_e32 v191, v190, v190
	v_fmac_f32_e32 v189, v188, v188
	v_add_f32_e32 v176, v183, v178
	v_add_f32_e32 v178, v187, v185
	v_fmac_f32_e32 v195, v194, v194
	v_fmac_f32_e32 v193, v192, v192
	v_add_f32_e32 v182, v191, v189
	s_waitcnt vmcnt(8) lgkmcnt(0)
	v_pk_fma_f32 v[88:89], v[232:233], s[0:1], v[88:89] op_sel_hi:[1,0,1]
	v_pk_fma_f32 v[86:87], v[230:231], s[0:1], v[86:87] op_sel_hi:[1,0,1]
	v_pk_fma_f32 v[56:57], v[236:237], s[0:1], v[56:57] op_sel_hi:[1,0,1]
	v_pk_fma_f32 v[54:55], v[234:235], s[0:1], v[54:55] op_sel_hi:[1,0,1]
	v_pk_fma_f32 v[28:29], v[240:241], s[0:1], v[28:29] op_sel_hi:[1,0,1]
	v_pk_fma_f32 v[26:27], v[238:239], s[0:1], v[26:27] op_sel_hi:[1,0,1]
	v_pk_fma_f32 v[8:9], v[244:245], s[0:1], v[8:9] op_sel_hi:[1,0,1]
	v_pk_fma_f32 v[6:7], v[242:243], s[0:1], v[6:7] op_sel_hi:[1,0,1]
	v_add_f32_e32 v176, v176, v178
	s_mov_b32 s100, 0x80000
	s_mov_b32 s101, 0
	v_lshl_add_u64 v[230:231], v[246:247], 0, s[100:101]
	global_load_dwordx4 v[234:237], v[230:231], off offset:64
	global_load_dwordx4 v[238:241], v[230:231], off offset:512
	global_load_dwordx4 v[242:245], v[230:231], off offset:576
	global_load_dwordx4 v[230:233], v[230:231], off
	v_or_b32_e32 v150, 48, v160
	v_ashrrev_i32_e32 v151, 31, v150
	v_lshlrev_b64 v[150:151], 12, v[150:151]
	v_lshl_add_u64 v[150:151], v[158:159], 0, v[150:151]
	v_add_f32_e32 v183, v195, v193
	v_add_f32_e32 v176, v182, v176
	v_add_f32_e32 v178, v183, v176
	ds_bpermute_b32 v182, v0, v178
	v_and_b32_e32 v176, 63, v172
	v_cmp_gt_u32_e32 vcc, 16, v176
	s_waitcnt lgkmcnt(0)
	v_add_f32_e32 v170, v178, v182
	ds_bpermute_b32 v171, v175, v170
	s_waitcnt vmcnt(8) lgkmcnt(0)
	v_pk_fma_f32 v[96:97], v[136:137], s[0:1], v[96:97] op_sel_hi:[1,0,1]
	v_pk_fma_f32 v[94:95], v[134:135], s[0:1], v[94:95] op_sel_hi:[1,0,1]
	v_pk_fma_f32 v[64:65], v[140:141], s[0:1], v[64:65] op_sel_hi:[1,0,1]
	v_pk_fma_f32 v[62:63], v[138:139], s[0:1], v[62:63] op_sel_hi:[1,0,1]
	v_pk_fma_f32 v[36:37], v[144:145], s[0:1], v[36:37] op_sel_hi:[1,0,1]
	v_pk_fma_f32 v[34:35], v[142:143], s[0:1], v[34:35] op_sel_hi:[1,0,1]
	v_pk_fma_f32 v[12:13], v[132:133], s[0:1], v[12:13] op_sel_hi:[1,0,1]
	v_pk_fma_f32 v[10:11], v[130:131], s[0:1], v[10:11] op_sel_hi:[1,0,1]
	s_nop 0
	s_mov_b32 s100, 0x90000
	s_mov_b32 s101, 0
	v_lshl_add_u64 v[134:135], v[246:247], 0, s[100:101]
	global_load_dwordx4 v[138:141], v[134:135], off offset:64
	global_load_dwordx4 v[142:145], v[134:135], off offset:512
	global_load_dwordx4 v[130:133], v[134:135], off offset:576
	global_load_dwordx4 v[134:137], v[134:135], off
	v_lshlrev_b64 v[150:151], 12, v[162:163]
	v_lshl_add_u64 v[150:151], v[158:159], 0, v[150:151]
	s_waitcnt vmcnt(8) lgkmcnt(0)
	v_pk_fma_f32 v[100:101], v[220:221], s[0:1], v[100:101] op_sel_hi:[1,0,1]
	v_pk_fma_f32 v[98:99], v[218:219], s[0:1], v[98:99] op_sel_hi:[1,0,1]
	v_pk_fma_f32 v[68:69], v[224:225], s[0:1], v[68:69] op_sel_hi:[1,0,1]
	v_pk_fma_f32 v[66:67], v[222:223], s[0:1], v[66:67] op_sel_hi:[1,0,1]
	v_pk_fma_f32 v[40:41], v[198:199], s[0:1], v[40:41] op_sel_hi:[1,0,1]
	v_pk_fma_f32 v[38:39], v[196:197], s[0:1], v[38:39] op_sel_hi:[1,0,1]
	v_pk_fma_f32 v[16:17], v[250:251], s[0:1], v[16:17] op_sel_hi:[1,0,1]
	v_pk_fma_f32 v[14:15], v[248:249], s[0:1], v[14:15] op_sel_hi:[1,0,1]
	s_nop 0
	s_mov_b32 s100, 0xa0000
	s_mov_b32 s101, 0
	v_lshl_add_u64 v[218:219], v[246:247], 0, s[100:101]
	global_load_dwordx4 v[222:225], v[218:219], off offset:64
	global_load_dwordx4 v[196:199], v[218:219], off offset:512
	global_load_dwordx4 v[248:251], v[218:219], off offset:576
	global_load_dwordx4 v[218:221], v[218:219], off
	s_waitcnt vmcnt(8) lgkmcnt(0)
	v_pk_fma_f32 v[104:105], v[232:233], s[0:1], v[104:105] op_sel_hi:[1,0,1]
	v_pk_fma_f32 v[102:103], v[230:231], s[0:1], v[102:103] op_sel_hi:[1,0,1]
	v_pk_fma_f32 v[72:73], v[236:237], s[0:1], v[72:73] op_sel_hi:[1,0,1]
	v_pk_fma_f32 v[70:71], v[234:235], s[0:1], v[70:71] op_sel_hi:[1,0,1]
	v_pk_fma_f32 v[48:49], v[240:241], s[0:1], v[48:49] op_sel_hi:[1,0,1]
	v_pk_fma_f32 v[46:47], v[238:239], s[0:1], v[46:47] op_sel_hi:[1,0,1]
	v_pk_fma_f32 v[24:25], v[244:245], s[0:1], v[24:25] op_sel_hi:[1,0,1]
	v_pk_fma_f32 v[22:23], v[242:243], s[0:1], v[22:23] op_sel_hi:[1,0,1]
	s_nop 0
	s_mov_b32 s100, 0xb0000
	s_mov_b32 s101, 0
	v_lshl_add_u64 v[230:231], v[246:247], 0, s[100:101]
	global_load_dwordx4 v[234:237], v[230:231], off offset:64
	global_load_dwordx4 v[238:241], v[230:231], off offset:512
	global_load_dwordx4 v[242:245], v[230:231], off offset:576
	global_load_dwordx4 v[230:233], v[230:231], off
	s_waitcnt vmcnt(8) lgkmcnt(0)
	v_pk_fma_f32 v[116:117], v[136:137], s[0:1], v[116:117] op_sel_hi:[1,0,1]
	v_pk_fma_f32 v[114:115], v[134:135], s[0:1], v[114:115] op_sel_hi:[1,0,1]
	v_pk_fma_f32 v[92:93], v[140:141], s[0:1], v[92:93] op_sel_hi:[1,0,1]
	v_pk_fma_f32 v[90:91], v[138:139], s[0:1], v[90:91] op_sel_hi:[1,0,1]
	v_pk_fma_f32 v[60:61], v[144:145], s[0:1], v[60:61] op_sel_hi:[1,0,1]
	v_pk_fma_f32 v[58:59], v[142:143], s[0:1], v[58:59] op_sel_hi:[1,0,1]
	v_pk_fma_f32 v[32:33], v[132:133], s[0:1], v[32:33] op_sel_hi:[1,0,1]
	v_pk_fma_f32 v[30:31], v[130:131], s[0:1], v[30:31] op_sel_hi:[1,0,1]
	s_nop 0
	s_waitcnt vmcnt(4) lgkmcnt(0)
	v_pk_fma_f32 v[128:129], v[220:221], s[0:1], v[128:129] op_sel_hi:[1,0,1]
	v_pk_fma_f32 v[126:127], v[218:219], s[0:1], v[126:127] op_sel_hi:[1,0,1]
	v_pk_fma_f32 v[112:113], v[224:225], s[0:1], v[112:113] op_sel_hi:[1,0,1]
	v_pk_fma_f32 v[110:111], v[222:223], s[0:1], v[110:111] op_sel_hi:[1,0,1]
	v_pk_fma_f32 v[84:85], v[198:199], s[0:1], v[84:85] op_sel_hi:[1,0,1]
	v_pk_fma_f32 v[82:83], v[196:197], s[0:1], v[82:83] op_sel_hi:[1,0,1]
	v_pk_fma_f32 v[52:53], v[250:251], s[0:1], v[52:53] op_sel_hi:[1,0,1]
	v_pk_fma_f32 v[50:51], v[248:249], s[0:1], v[50:51] op_sel_hi:[1,0,1]
	s_nop 0
	s_waitcnt vmcnt(0) lgkmcnt(0)
	v_pk_fma_f32 v[124:125], v[232:233], s[0:1], v[124:125] op_sel_hi:[1,0,1]
	v_pk_fma_f32 v[122:123], v[230:231], s[0:1], v[122:123] op_sel_hi:[1,0,1]
	v_pk_fma_f32 v[120:121], v[236:237], s[0:1], v[120:121] op_sel_hi:[1,0,1]
	v_pk_fma_f32 v[118:119], v[234:235], s[0:1], v[118:119] op_sel_hi:[1,0,1]
	v_pk_fma_f32 v[108:109], v[240:241], s[0:1], v[108:109] op_sel_hi:[1,0,1]
	v_pk_fma_f32 v[106:107], v[238:239], s[0:1], v[106:107] op_sel_hi:[1,0,1]
	v_pk_fma_f32 v[80:81], v[244:245], s[0:1], v[80:81] op_sel_hi:[1,0,1]
	v_pk_fma_f32 v[78:79], v[242:243], s[0:1], v[78:79] op_sel_hi:[1,0,1]
	s_lshl_b32 s0, s46, 3
	s_add_i32 s2, s16, s0
	s_and_saveexec_b64 s[0:1], vcc
	s_mul_i32 s60, s36, 0x600
	v_readlane_b32 s61, v252, 14
	v_readlane_b32 s53, v252, 16
	v_readlane_b32 s54, v252, 17
	s_movk_i32 s55, 0x6000
	s_mov_b32 s58, 0x3fb8aa3b
	s_movk_i32 s59, 0xe80
	s_mov_b32 s63, 0xc2fc0000
	s_mov_b32 s66, 0x1ffff
	s_movk_i32 s67, 0x1ff
	s_cbranch_execz .LBB0_1533
	s_lshl_b32 s3, s44, 11
	s_add_i32 s3, s2, s3
	v_mul_f32_e32 v130, 0x3c800000, v177
	v_add_f32_e32 v131, v170, v171
	v_lshl_add_u32 v132, v173, 5, s3
	ds_write_b64 v132, v[130:131]

.LBB0_1570:
	s_or_b64 exec, exec, s[0:1]
	s_add_i32 s0, s33, 0x200d0
	s_waitcnt lgkmcnt(0)
	s_barrier
	v_mov_b32_e32 v0, s0
	ds_read_b64 v[130:131], v0
	v_readlane_b32 s0, v252, 6
	s_lshl_b32 s44, s0, 10
	s_lshl_b64 s[0:1], s[44:45], 2
	v_lshlrev_b64 v[132:133], 2, v[146:147]
	s_waitcnt lgkmcnt(0)
	v_readfirstlane_b32 s2, v130
	v_readfirstlane_b32 s3, v131
	s_add_u32 s2, s2, s0
	s_addc_u32 s3, s3, s1
	s_add_i32 s4, s33, 0x200d8
	v_mov_b32_e32 v0, s4
	ds_read_b64 v[130:131], v0
	v_lshl_add_u64 v[140:141], s[2:3], 0, v[132:133]
	v_lshl_add_u32 v0, v174, 3, s16
	v_readlane_b32 s6, v252, 21
	v_readlane_b32 s7, v252, 22
	s_waitcnt lgkmcnt(0)
	v_readfirstlane_b32 s3, v130
	v_readfirstlane_b32 s2, v131
	s_add_u32 s0, s3, s0
	s_addc_u32 s1, s2, s1
	v_lshl_add_u64 v[142:143], s[0:1], 0, v[132:133]
	flat_load_dwordx4 v[130:133], v[140:141]
	flat_load_dwordx4 v[134:137], v[142:143]
	global_load_dwordx4 v[182:185], v[140:141], off offset:64
	global_load_dwordx4 v[186:189], v[142:143], off offset:64
	global_load_dwordx4 v[190:193], v[140:141], off offset:512
	global_load_dwordx4 v[194:197], v[142:143], off offset:512
	global_load_dwordx4 v[218:221], v[140:141], off offset:576
	global_load_dwordx4 v[222:225], v[142:143], off offset:576
	ds_read_b64 v[170:171], v0 offset:8192
	v_cndmask_b32_e64 v145, 0, 1, s[6:7]
	s_add_u32 s0, s23, 0x4bf0000
	v_cmp_eq_u32_e64 s[4:5], 0, v144
	v_lshlrev_b64 v[138:139], 10, v[160:161]
	s_waitcnt lgkmcnt(0)
	v_sub_f32_e32 v77, v77, v170
	v_sub_f32_e32 v76, v76, v170
	v_sub_f32_e32 v75, v75, v170
	v_sub_f32_e32 v74, v74, v170
	v_pk_mul_f32 v[74:75], v[170:171], v[74:75] op_sel:[1,0]
	v_pk_mul_f32 v[76:77], v[170:171], v[76:77] op_sel:[1,0]
	v_cmp_ne_u32_e64 s[2:3], 1, v145
	s_addc_u32 s1, s22, 0
	s_andn2_b64 vcc, exec, s[6:7]
	s_waitcnt vmcnt(0)
	v_pk_fma_f32 v[76:77], v[132:133], v[76:77], v[136:137]
	v_pk_fma_f32 v[74:75], v[130:131], v[74:75], v[134:135]
	v_cndmask_b32_e64 v77, v211, v77, s[4:5]
	v_cndmask_b32_e64 v76, v211, v76, s[4:5]
	v_cndmask_b32_e64 v75, v211, v75, s[4:5]
	v_cndmask_b32_e64 v74, v211, v74, s[4:5]
	flat_store_dwordx4 v[148:149], v[74:77]
	s_cbranch_vccnz .LBB0_1572
	v_lshl_add_u64 v[144:145], v[138:139], 0, v[146:147]
	v_cvt_pk_bf16_f32 v74, v74, v75
	v_cvt_pk_bf16_f32 v75, v76, v77
	v_lshl_add_u64 v[76:77], v[144:145], 1, s[0:1]
	flat_store_dwordx2 v[76:77], v[74:75]
